# v48 plus the four in-phase hand-offs (P0 modulation counter, P3 state counters, P6/P9 LayerNorm panel counters): consumer acquire invalidate issued before the first poll instead of after it succeeds
# baseline (speedup 1.0000x reference)
.LBB0_63:
	s_add_i32 s0, s12, 0xfffff000
	s_ashr_i32 s13, s12, 31
	s_cmpk_lt_i32 s12, 0x1000
	s_cselect_b64 s[30:31], -1, 0
	s_and_b64 s[4:5], s[30:31], exec
	s_cselect_b32 s5, s13, 0
	s_cselect_b32 s4, s12, s0
	s_cselect_b32 s1, s57, s59
	s_cselect_b32 s3, s56, s58
	s_lshl_b64 s[4:5], s[4:5], 12
	s_add_u32 s4, s3, s4
	s_addc_u32 s5, s1, s5
	s_add_i32 s28, s12, 0x600
	v_mov_b32_e32 v34, v214
	s_add_i32 s10, s12, 0xfffff600
	s_ashr_i32 s29, s28, 31
	s_cmpk_lt_i32 s12, 0xa00
	v_ashrrev_i32_e32 v35, 31, v34
	v_lshlrev_b64 v[94:95], 4, v[34:35]
	s_cselect_b64 s[68:69], -1, 0
	v_lshl_add_u64 v[6:7], s[4:5], 0, v[94:95]
	s_and_b64 s[4:5], s[68:69], exec
	s_cselect_b32 s5, s29, 0
	s_cselect_b32 s4, s28, s10
	s_cselect_b32 s1, s57, s59
	s_cselect_b32 s3, s56, s58
	s_lshl_b64 s[4:5], s[4:5], 12
	s_add_u32 s4, s3, s4
	s_addc_u32 s5, s1, s5
	v_lshl_add_u64 v[14:15], s[4:5], 0, v[94:95]
	global_load_dwordx4 v[18:21], v[6:7], off
	global_load_dwordx4 v[10:13], v[6:7], off offset:1024
	global_load_dwordx4 v[2:5], v[6:7], off offset:2048
	s_nop 0
	global_load_dwordx4 v[6:9], v[6:7], off offset:3072
	s_nop 0
	global_load_dwordx4 v[30:33], v[14:15], off
	global_load_dwordx4 v[26:29], v[14:15], off offset:1024
	global_load_dwordx4 v[22:25], v[14:15], off offset:2048
	s_nop 0
	global_load_dwordx4 v[14:17], v[14:15], off offset:3072
	s_and_saveexec_b64 s[6:7], s[14:15]
	s_cbranch_execz .LBB0_78
	buffer_inv sc1
	s_mov_b32 s1, 0x100000
	v_mov_b32_e32 v1, 0
	s_branch .LBB0_67

.LBB0_67:
	global_load_dword v36, v1, s[8:9] sc1
	s_mov_b64 s[20:21], -1
	s_waitcnt vmcnt(0)
	v_cmp_lt_u32_e32 vcc, 63, v36
	s_cbranch_vccnz .LBB0_66
	s_cmp_lg_u32 s1, 0
	s_sleep 2
	s_cbranch_scc0 .LBB0_65
	global_load_dword v36, v1, s[8:9] sc1
	s_waitcnt vmcnt(0)
	v_cmp_gt_u32_e32 vcc, 64, v36
	s_cbranch_vccz .LBB0_66
	s_sleep 2
	global_load_dword v36, v1, s[8:9] sc1
	s_waitcnt vmcnt(0)
	v_cmp_gt_u32_e32 vcc, 64, v36
	s_cbranch_vccz .LBB0_66
	s_sleep 2
	global_load_dword v36, v1, s[8:9] sc1
	s_waitcnt vmcnt(0)
	v_cmp_gt_u32_e32 vcc, 64, v36
	s_cbranch_vccz .LBB0_66
	s_sleep 2
	global_load_dword v36, v1, s[8:9] sc1
	s_waitcnt vmcnt(0)
	v_cmp_gt_u32_e32 vcc, 64, v36
	s_cbranch_vccz .LBB0_66
	s_sleep 2
	global_load_dword v36, v1, s[8:9] sc1
	s_waitcnt vmcnt(0)
	v_cmp_gt_u32_e32 vcc, 64, v36
	s_cbranch_vccz .LBB0_66
	s_sleep 2
	global_load_dword v36, v1, s[8:9] sc1
	s_waitcnt vmcnt(0)
	v_cmp_gt_u32_e32 vcc, 64, v36
	s_cbranch_vccz .LBB0_66
	s_sleep 2
	global_load_dword v36, v1, s[8:9] sc1
	s_waitcnt vmcnt(0)
	v_cmp_gt_u32_e32 vcc, 64, v36
	s_cbranch_vccz .LBB0_66
	s_sleep 2
	s_add_i32 s1, s1, -8
	s_mov_b64 s[20:21], 0
	s_branch .LBB0_66
.LBB0_77:
	s_waitcnt vmcnt(0)
.LBB0_78:
	s_or_b64 exec, exec, s[6:7]
	s_waitcnt vmcnt(7)
	v_mov_b32_e32 v58, v19
	v_mov_b32_e32 v59, v20
	v_mov_b32_e32 v64, v18
	v_mov_b32_e32 v65, v21
	v_pk_add_f32 v[58:59], v[58:59], v[64:65]
	s_waitcnt vmcnt(6)
	v_mov_b32_e32 v64, v11
	v_mov_b32_e32 v65, v12
	v_mov_b32_e32 v66, v10
	v_mov_b32_e32 v67, v13
	v_pk_add_f32 v[64:65], v[64:65], v[66:67]
	v_add_f32_e32 v58, v58, v59
	v_pk_add_f32 v[64:65], v[64:65], v[64:65] op_sel_hi:[0,1]
	v_add_f32_e32 v59, 0, v58
	s_waitcnt vmcnt(5)
	v_add_f32_e32 v67, v2, v3
	v_add_f32_e32 v69, v4, v5
	s_waitcnt vmcnt(4)
	v_mov_b32_e32 v66, v6
	v_mov_b32_e32 v68, v7
	v_mov_b32_e32 v64, v8
	v_mov_b32_e32 v58, v9
	v_mbcnt_lo_u32_b32 v1, -1, 0
	v_pk_add_f32 v[66:67], v[66:67], v[68:69]
	v_pk_add_f32 v[58:59], v[64:65], v[58:59]
	v_mbcnt_hi_u32_b32 v36, -1, v1
	v_pk_add_f32 v[58:59], v[66:67], v[58:59]
	v_and_b32_e32 v37, 64, v36
	v_add_f32_e32 v58, v58, v59
	v_xor_b32_e32 v1, 16, v36
	v_add_u32_e32 v37, 64, v37
	v_add_f32_dpp v58, v58, v58 quad_perm:[1,0,3,2] row_mask:0xf bank_mask:0xf bound_ctrl:1
	v_cmp_lt_i32_e32 vcc, v1, v37
	v_xor_b32_e32 v38, 32, v36
	v_add_f32_dpp v58, v58, v58 quad_perm:[2,3,0,1] row_mask:0xf bank_mask:0xf bound_ctrl:1
	v_cndmask_b32_e32 v1, v36, v1, vcc
	v_lshlrev_b32_e32 v1, 2, v1
	v_add_f32_dpp v58, v58, v58 row_half_mirror row_mask:0xf bank_mask:0xf bound_ctrl:1
	v_cmp_lt_i32_e32 vcc, v38, v37
	s_add_i32 s4, s12, 0xe00
	v_add_f32_dpp v58, v58, v58 row_mirror row_mask:0xf bank_mask:0xf bound_ctrl:1
	ds_bpermute_b32 v59, v1, v58
	v_cndmask_b32_e32 v36, v36, v38, vcc
	v_lshlrev_b32_e32 v96, 2, v36
	s_lshr_b32 s1, s4, 11
	s_mulk_i32 s1, 0x1800
	s_waitcnt lgkmcnt(0)
	v_add_f32_e32 v97, v58, v59
	ds_bpermute_b32 v100, v96, v97
	s_add_i32 s20, s12, 0x1e00
	s_add_i32 s5, s1, 0x1800
	s_cmpk_lt_i32 s12, 0xf200
	s_cselect_b32 s1, s57, s59
	s_waitcnt lgkmcnt(0)
	v_add_f32_e32 v97, v97, v100
	v_fmamk_f32 v19, v97, 0xba800000, v19
	v_fmamk_f32 v18, v97, 0xba800000, v18
	v_fmamk_f32 v21, v97, 0xba800000, v21
	v_fmac_f32_e32 v20, 0xba800000, v97
	v_pk_mul_f32 v[100:101], v[20:21], v[20:21]
	v_pk_mul_f32 v[102:103], v[18:19], v[18:19]
	s_cselect_b32 s3, s56, s58
	s_cselect_b32 s22, 0, s5
	s_ashr_i32 s21, s20, 31
	v_pk_mov_b32 v[104:105], v[102:103], v[100:101] op_sel:[1,0]
	v_mov_b32_e32 v103, v101
	s_cmpk_lt_i32 s12, 0xf200
	v_pk_add_f32 v[100:101], v[104:105], v[102:103]
	v_fmamk_f32 v11, v97, 0xba800000, v11
	v_fmamk_f32 v10, v97, 0xba800000, v10
	v_fmamk_f32 v13, v97, 0xba800000, v13
	v_fmac_f32_e32 v12, 0xba800000, v97
	s_cselect_b32 s26, s20, s4
	s_cselect_b32 s27, s21, 0
	s_add_i32 s6, s12, 0x200
	v_pk_add_f32 v[100:101], v[100:101], v[100:101] op_sel_hi:[0,1]
	v_pk_mul_f32 v[102:103], v[12:13], v[12:13]
	v_pk_mul_f32 v[104:105], v[10:11], v[10:11]
	v_fmamk_f32 v2, v97, 0xba800000, v2
	s_waitcnt vmcnt(3)
	v_mov_b32_e32 v108, v31
	v_mov_b32_e32 v109, v32
	v_mov_b32_e32 v110, v30
	v_mov_b32_e32 v111, v33
	s_lshr_b32 s4, s6, 11
	v_pk_mov_b32 v[106:107], v[104:105], v[102:103] op_sel:[1,0]
	v_mov_b32_e32 v105, v103
	v_fmamk_f32 v3, v97, 0xba800000, v3
	v_fmac_f32_e32 v4, 0xba800000, v97
	v_mul_f32_e32 v100, v2, v2
	v_pk_add_f32 v[108:109], v[108:109], v[110:111]
	s_waitcnt vmcnt(2)
	v_mov_b32_e32 v110, v27
	v_mov_b32_e32 v111, v28
	v_mov_b32_e32 v112, v26
	v_mov_b32_e32 v113, v29
	s_mulk_i32 s4, 0x1800
	v_pk_add_f32 v[102:103], v[106:107], v[104:105]
	v_fmamk_f32 v5, v97, 0xba800000, v5
	v_pk_fma_f32 v[104:105], v[2:3], v[2:3], v[100:101] op_sel_hi:[1,1,0]
	v_mul_f32_e32 v100, v4, v4
	v_pk_add_f32 v[110:111], v[110:111], v[112:113]
	s_add_i32 s24, s12, 0x1200
	s_add_i32 s8, s4, 0x1800
	v_pk_fma_f32 v[106:107], v[4:5], v[4:5], v[100:101] op_sel_hi:[1,1,0]
	v_add_f32_e32 v100, v108, v109
	v_pk_add_f32 v[110:111], v[110:111], v[110:111] op_sel_hi:[0,1]
	s_cmpk_lt_i32 s12, 0xfe00
	v_add_f32_e32 v109, 0, v100
	s_waitcnt vmcnt(1)
	v_add_f32_e32 v113, v22, v23
	v_add_f32_e32 v115, v24, v25
	s_waitcnt vmcnt(0)
	v_mov_b32_e32 v112, v14
	v_mov_b32_e32 v114, v15
	v_mov_b32_e32 v110, v16
	v_mov_b32_e32 v108, v17
	s_cselect_b32 s4, s57, s59
	s_cselect_b32 s5, s56, s58
	s_cselect_b32 s34, 0, s8
	s_ashr_i32 s25, s24, 31
	v_pk_add_f32 v[112:113], v[112:113], v[114:115]
	v_pk_add_f32 v[108:109], v[110:111], v[108:109]
	s_cmpk_lt_i32 s12, 0xfe00
	v_pk_add_f32 v[108:109], v[112:113], v[108:109]
	s_cselect_b32 s36, s24, s6
	s_cselect_b32 s37, s25, 0
	s_lshr_b32 s0, s0, 11
	v_add_f32_e32 v100, v108, v109
	s_mulk_i32 s0, 0x1800
	s_addk_i32 s0, 0x1800
	v_add_f32_dpp v100, v100, v100 quad_perm:[1,0,3,2] row_mask:0xf bank_mask:0xf bound_ctrl:1
	s_and_b64 s[8:9], s[30:31], exec
	v_pk_add_f32 v[102:103], v[102:103], v[102:103] op_sel_hi:[0,1]
	v_add_f32_dpp v100, v100, v100 quad_perm:[2,3,0,1] row_mask:0xf bank_mask:0xf bound_ctrl:1
	s_mov_b32 s7, 0
	s_cselect_b32 s6, 0, s0
	v_add_f32_dpp v100, v100, v100 row_half_mirror row_mask:0xf bank_mask:0xf bound_ctrl:1
	s_lshl_b64 s[8:9], s[6:7], 2
	v_readlane_b32 s70, v242, 34
	v_add_f32_dpp v102, v100, v100 row_mirror row_mask:0xf bank_mask:0xf bound_ctrl:1
	ds_bpermute_b32 v108, v1, v102
	v_readlane_b32 s71, v242, 35
	s_add_u32 s8, s70, s8
	s_addc_u32 s9, s71, s9
	s_lshr_b32 s0, s10, 11
	s_mulk_i32 s0, 0x1800
	s_addk_i32 s0, 0x1800
	s_and_b64 s[10:11], s[68:69], exec
	v_fmamk_f32 v9, v97, 0xba800000, v9
	v_fmamk_f32 v8, v97, 0xba800000, v8
	v_fmamk_f32 v7, v97, 0xba800000, v7
	v_fmac_f32_e32 v6, 0xba800000, v97
	s_waitcnt lgkmcnt(0)
	v_add_f32_e32 v97, v102, v108
	v_lshl_add_u64 v[92:93], v[34:35], 3, s[66:67]
	s_cselect_b32 s6, 0, s0
	v_lshl_add_u64 v[34:35], s[8:9], 0, v[94:95]
	s_movk_i32 s0, 0x1000
	ds_bpermute_b32 v108, v96, v97
	s_mov_b64 s[8:9], 0x1000
	v_add_co_u32_e32 v42, vcc, s0, v34
	v_lshl_add_u64 v[40:41], v[34:35], 0, s[8:9]
	s_nop 0
	v_addc_co_u32_e32 v43, vcc, 0, v35, vcc
	s_waitcnt lgkmcnt(0)
	s_barrier
	global_load_dwordx4 v[72:75], v[34:35], off
	global_load_dwordx4 v[52:55], v[34:35], off offset:1024
	global_load_dwordx4 v[60:63], v[40:41], off offset:1024
	global_load_dwordx4 v[48:51], v[40:41], off offset:2048
	global_load_dwordx4 v[44:47], v[34:35], off offset:2048
	global_load_dwordx4 v[36:39], v[34:35], off offset:3072
	global_load_dwordx4 v[80:83], v[42:43], off
	s_nop 0
	global_load_dwordx4 v[40:43], v[40:41], off offset:3072
	v_mul_f32_e32 v104, v6, v6
	v_mul_f32_e32 v106, v7, v7
	v_mul_f32_e32 v100, v8, v8
	v_mul_f32_e32 v102, v9, v9
	v_add_f32_e32 v97, v97, v108
	v_pk_add_f32 v[104:105], v[104:105], v[106:107]
	v_pk_add_f32 v[100:101], v[100:101], v[102:103]
	v_fmamk_f32 v31, v97, 0xba800000, v31
	v_fmamk_f32 v30, v97, 0xba800000, v30
	v_fmamk_f32 v33, v97, 0xba800000, v33
	v_fmac_f32_e32 v32, 0xba800000, v97
	v_pk_add_f32 v[106:107], v[104:105], v[100:101]
	v_pk_mul_f32 v[100:101], v[32:33], v[32:33]
	v_pk_mul_f32 v[102:103], v[30:31], v[30:31]
	v_fmamk_f32 v109, v97, 0xba800000, v27
	v_pk_mov_b32 v[104:105], v[102:103], v[100:101] op_sel:[1,0]
	v_mov_b32_e32 v103, v101
	v_fmamk_f32 v108, v97, 0xba800000, v26
	v_fmamk_f32 v29, v97, 0xba800000, v29
	v_fmac_f32_e32 v28, 0xba800000, v97
	v_pk_add_f32 v[100:101], v[104:105], v[102:103]
	v_pk_mul_f32 v[26:27], v[28:29], v[28:29]
	v_pk_mul_f32 v[102:103], v[108:109], v[108:109]
	v_fmamk_f32 v110, v97, 0xba800000, v22
	v_pk_mov_b32 v[104:105], v[102:103], v[26:27] op_sel:[1,0]
	v_mov_b32_e32 v103, v27
	v_fmac_f32_e32 v24, 0xba800000, v97
	v_pk_add_f32 v[26:27], v[104:105], v[102:103]
	v_fmamk_f32 v111, v97, 0xba800000, v23
	v_fmamk_f32 v25, v97, 0xba800000, v25
	v_mul_f32_e32 v22, v110, v110
	v_fmamk_f32 v112, v97, 0xba800000, v16
	v_mul_f32_e32 v16, v24, v24
	v_pk_add_f32 v[100:101], v[100:101], v[100:101] op_sel_hi:[0,1]
	v_pk_add_f32 v[26:27], v[26:27], v[26:27] op_sel_hi:[0,1]
	v_pk_fma_f32 v[22:23], v[110:111], v[110:111], v[22:23] op_sel_hi:[1,1,0]
	v_fmamk_f32 v113, v97, 0xba800000, v17
	v_fmamk_f32 v15, v97, 0xba800000, v15
	v_fmac_f32_e32 v14, 0xba800000, v97
	v_pk_fma_f32 v[16:17], v[24:25], v[24:25], v[16:17] op_sel_hi:[1,1,0]
	v_mul_f32_e32 v22, v14, v14
	v_mul_f32_e32 v16, v15, v15
	v_mul_f32_e32 v100, v112, v112
	v_mul_f32_e32 v26, v113, v113
	v_pk_add_f32 v[16:17], v[22:23], v[16:17]
	v_pk_add_f32 v[22:23], v[100:101], v[26:27]
	v_add_f32_e32 v26, v106, v107
	s_lshl_b64 s[10:11], s[6:7], 2
	s_add_u32 s10, s70, s10
	v_add_f32_dpp v26, v26, v26 quad_perm:[1,0,3,2] row_mask:0xf bank_mask:0xf bound_ctrl:1
	v_pk_add_f32 v[16:17], v[16:17], v[22:23]
	s_addc_u32 s11, s71, s11
	v_add_f32_dpp v26, v26, v26 quad_perm:[2,3,0,1] row_mask:0xf bank_mask:0xf bound_ctrl:1
	v_add_f32_e32 v16, v16, v17
	v_lshl_add_u64 v[56:57], s[10:11], 0, v[94:95]
	v_add_f32_dpp v26, v26, v26 row_half_mirror row_mask:0xf bank_mask:0xf bound_ctrl:1
	v_add_f32_dpp v16, v16, v16 quad_perm:[1,0,3,2] row_mask:0xf bank_mask:0xf bound_ctrl:1
	v_add_co_u32_e32 v98, vcc, s0, v56
	v_add_f32_dpp v26, v26, v26 row_mirror row_mask:0xf bank_mask:0xf bound_ctrl:1
	ds_bpermute_b32 v27, v1, v26
	v_add_f32_dpp v16, v16, v16 quad_perm:[2,3,0,1] row_mask:0xf bank_mask:0xf bound_ctrl:1
	v_lshl_add_u64 v[34:35], v[56:57], 0, s[8:9]
	v_addc_co_u32_e32 v99, vcc, 0, v57, vcc
	s_waitcnt lgkmcnt(0)
	v_add_f32_e32 v26, v26, v27
	ds_bpermute_b32 v27, v96, v26
	v_add_f32_dpp v16, v16, v16 row_half_mirror row_mask:0xf bank_mask:0xf bound_ctrl:1
	global_load_dwordx4 v[88:91], v[56:57], off
	global_load_dwordx4 v[76:79], v[56:57], off offset:1024
	global_load_dwordx4 v[84:87], v[34:35], off offset:1024
	global_load_dwordx4 v[68:71], v[34:35], off offset:2048
	global_load_dwordx4 v[64:67], v[56:57], off offset:2048
	s_nop 0
	global_load_dwordx4 v[56:59], v[56:57], off offset:3072
	s_nop 0
	global_load_dwordx4 v[98:101], v[98:99], off
	s_nop 0
	global_load_dwordx4 v[102:105], v[34:35], off offset:3072
	s_waitcnt lgkmcnt(0)
	v_add_f32_e32 v26, v26, v27
	v_mov_b32_e32 v97, 0x3727c5ac
	v_add_f32_dpp v23, v16, v16 row_mirror row_mask:0xf bank_mask:0xf bound_ctrl:1
	v_fmamk_f32 v26, v26, 0x3a800000, v97
	ds_bpermute_b32 v34, v1, v23
	v_rsq_f32_e32 v22, v26
	s_add_i32 s6, s12, 0xfffffc00
	s_lshr_b32 s10, s6, 11
	s_add_i32 s30, s12, 0xc00
	s_mulk_i32 s10, 0x1800
	v_pk_mul_f32 v[106:107], v[10:11], v[22:23] op_sel_hi:[1,0]
	s_waitcnt lgkmcnt(0)
	v_add_f32_e32 v10, v23, v34
	s_ashr_i32 s31, s30, 31
	s_add_i32 s23, s10, 0x1800
	ds_bpermute_b32 v11, v96, v10
	s_cmpk_lt_i32 s12, 0x400
	s_cselect_b32 s11, s31, 0
	s_cselect_b32 s10, s30, s6
	s_cselect_b32 s35, s57, s59
	s_cselect_b32 s68, s56, s58
	s_cselect_b32 s6, 0, s23
	s_lshl_b64 s[10:11], s[10:11], 12
	s_add_u32 s10, s68, s10
	s_addc_u32 s11, s35, s11
	v_pk_mul_f32 v[116:117], v[2:3], v[22:23] op_sel_hi:[1,0]
	s_waitcnt lgkmcnt(0)
	v_add_f32_e32 v2, v10, v11
	v_lshl_add_u64 v[16:17], s[10:11], 0, v[94:95]
	v_fmamk_f32 v2, v2, 0x3a800000, v97
	v_pk_mul_f32 v[118:119], v[4:5], v[22:23] op_sel_hi:[1,0]
	v_pk_mul_f32 v[120:121], v[6:7], v[22:23] op_sel_hi:[1,0]
	v_rsq_f32_e32 v34, v2
	v_pk_mul_f32 v[122:123], v[8:9], v[22:23] op_sel_hi:[1,0]
	global_load_dwordx4 v[6:9], v[16:17], off
	global_load_dwordx4 v[2:5], v[16:17], off offset:1024
	v_pk_mul_f32 v[26:27], v[18:19], v[22:23] op_sel_hi:[1,0]
	v_pk_mul_f32 v[114:115], v[12:13], v[22:23] op_sel_hi:[1,0]
	global_load_dwordx4 v[10:13], v[16:17], off offset:2048
	s_nop 0
	global_load_dwordx4 v[16:19], v[16:17], off offset:3072
	s_lshl_b64 s[10:11], s[36:37], 12
	s_add_u32 s10, s5, s10
	s_addc_u32 s11, s4, s11
	v_pk_mul_f32 v[20:21], v[20:21], v[22:23] op_sel_hi:[1,0]
	v_pk_mul_f32 v[126:127], v[28:29], v[34:35] op_sel_hi:[1,0]
	v_pk_mul_f32 v[128:129], v[24:25], v[34:35] op_sel_hi:[1,0]
	s_waitcnt vmcnt(13)
	v_pk_add_f32 v[22:23], v[82:83], 1.0 op_sel_hi:[1,0]
	v_pk_add_f32 v[24:25], v[80:81], 1.0 op_sel_hi:[1,0]
	v_lshl_add_u64 v[28:29], s[10:11], 0, v[94:95]
	v_pk_mul_f32 v[124:125], v[32:33], v[34:35] op_sel_hi:[1,0]
	v_pk_fma_f32 v[32:33], v[22:23], v[20:21], v[74:75]
	v_pk_fma_f32 v[72:73], v[24:25], v[26:27], v[72:73]
	global_load_dwordx4 v[24:27], v[28:29], off
	global_load_dwordx4 v[20:23], v[28:29], off offset:1024
	v_pk_mul_f32 v[14:15], v[14:15], v[34:35] op_sel_hi:[1,0]
	v_pk_mul_f32 v[74:75], v[30:31], v[34:35] op_sel_hi:[1,0]
	v_pk_mul_f32 v[80:81], v[108:109], v[34:35] op_sel_hi:[1,0]
	v_pk_mul_f32 v[82:83], v[110:111], v[34:35] op_sel_hi:[1,0]
	v_pk_mul_f32 v[108:109], v[112:113], v[34:35] op_sel_hi:[1,0]
	v_cvt_pk_bf16_f32 v72, v72, v73
	v_cvt_pk_bf16_f32 v73, v32, v33
	global_load_dwordx4 v[32:35], v[28:29], off offset:2048
	s_nop 0
	global_load_dwordx4 v[28:31], v[28:29], off offset:3072
	s_waitcnt vmcnt(16)
	v_pk_add_f32 v[42:43], v[42:43], 1.0 op_sel_hi:[1,0]
	v_pk_add_f32 v[40:41], v[40:41], 1.0 op_sel_hi:[1,0]
	s_lshl_b64 s[4:5], s[12:13], 11
	v_pk_fma_f32 v[38:39], v[42:43], v[122:123], v[38:39]
	v_pk_fma_f32 v[36:37], v[40:41], v[120:121], v[36:37]
	v_lshl_add_u64 v[110:111], v[92:93], 0, s[4:5]
	v_cvt_pk_bf16_f32 v36, v36, v37
	v_cvt_pk_bf16_f32 v37, v38, v39
	s_lshl_b64 s[4:5], s[28:29], 11
	global_store_dwordx2 v[110:111], v[36:37], off offset:1536
	v_lshl_add_u64 v[36:37], v[92:93], 0, s[4:5]
	s_lshl_b64 s[4:5], s[6:7], 2
	s_add_u32 s4, s70, s4
	v_pk_add_f32 v[60:61], v[60:61], 1.0 op_sel_hi:[1,0]
	v_pk_add_f32 v[48:49], v[48:49], 1.0 op_sel_hi:[1,0]
	s_addc_u32 s5, s71, s5
	v_pk_add_f32 v[62:63], v[62:63], 1.0 op_sel_hi:[1,0]
	v_pk_fma_f32 v[52:53], v[60:61], v[106:107], v[52:53]
	v_pk_add_f32 v[50:51], v[50:51], 1.0 op_sel_hi:[1,0]
	v_pk_fma_f32 v[44:45], v[48:49], v[116:117], v[44:45]
	global_store_dwordx2 v[110:111], v[72:73], off
	s_waitcnt vmcnt(11)
	v_pk_add_f32 v[40:41], v[98:99], 1.0 op_sel_hi:[1,0]
	v_pk_add_f32 v[38:39], v[100:101], 1.0 op_sel_hi:[1,0]
	v_pk_fma_f32 v[40:41], v[40:41], v[74:75], v[88:89]
	v_pk_fma_f32 v[38:39], v[38:39], v[124:125], v[90:91]
	v_cvt_pk_bf16_f32 v40, v40, v41
	v_pk_fma_f32 v[54:55], v[62:63], v[114:115], v[54:55]
	v_cvt_pk_bf16_f32 v41, v38, v39
	global_store_dwordx2 v[36:37], v[40:41], off
	v_pk_add_f32 v[40:41], v[84:85], 1.0 op_sel_hi:[1,0]
	v_pk_add_f32 v[38:39], v[86:87], 1.0 op_sel_hi:[1,0]
	v_pk_fma_f32 v[40:41], v[40:41], v[80:81], v[76:77]
	v_pk_fma_f32 v[38:39], v[38:39], v[126:127], v[78:79]
	v_cvt_pk_bf16_f32 v40, v40, v41
	v_cvt_pk_bf16_f32 v52, v52, v53
	v_cvt_pk_bf16_f32 v53, v54, v55
	global_store_dwordx2 v[110:111], v[52:53], off offset:512
	v_cvt_pk_bf16_f32 v41, v38, v39
	global_store_dwordx2 v[36:37], v[40:41], off offset:512
	v_pk_add_f32 v[40:41], v[68:69], 1.0 op_sel_hi:[1,0]
	v_pk_add_f32 v[38:39], v[70:71], 1.0 op_sel_hi:[1,0]
	v_pk_fma_f32 v[40:41], v[40:41], v[82:83], v[64:65]
	v_pk_fma_f32 v[38:39], v[38:39], v[128:129], v[66:67]
	v_cvt_pk_bf16_f32 v40, v40, v41
	v_pk_fma_f32 v[46:47], v[50:51], v[118:119], v[46:47]
	v_cvt_pk_bf16_f32 v41, v38, v39
	global_store_dwordx2 v[36:37], v[40:41], off offset:1024
	s_waitcnt vmcnt(14)
	v_pk_add_f32 v[40:41], v[102:103], 1.0 op_sel_hi:[1,0]
	v_pk_add_f32 v[38:39], v[104:105], 1.0 op_sel_hi:[1,0]
	v_pk_fma_f32 v[14:15], v[40:41], v[14:15], v[56:57]
	v_pk_fma_f32 v[38:39], v[38:39], v[108:109], v[58:59]
	v_cvt_pk_bf16_f32 v14, v14, v15
	v_cvt_pk_bf16_f32 v44, v44, v45
	v_cvt_pk_bf16_f32 v45, v46, v47
	global_store_dwordx2 v[110:111], v[44:45], off offset:1024
	v_cvt_pk_bf16_f32 v15, v38, v39
	global_store_dwordx2 v[36:37], v[14:15], off offset:1536
	v_lshl_add_u64 v[14:15], s[4:5], 0, v[94:95]
	v_add_co_u32_e32 v62, vcc, s0, v14
	v_lshl_add_u64 v[60:61], v[14:15], 0, s[8:9]
	s_nop 0
	v_addc_co_u32_e32 v63, vcc, 0, v15, vcc
	global_load_dwordx4 v[56:59], v[14:15], off
	global_load_dwordx4 v[48:51], v[14:15], off offset:1024
	global_load_dwordx4 v[52:55], v[60:61], off offset:1024
	global_load_dwordx4 v[44:47], v[60:61], off offset:2048
	global_load_dwordx4 v[40:43], v[14:15], off offset:2048
	global_load_dwordx4 v[36:39], v[14:15], off offset:3072
	s_waitcnt vmcnt(21)
	v_mov_b32_e32 v14, v7
	v_mov_b32_e32 v15, v8
	v_mov_b32_e32 v64, v6
	v_mov_b32_e32 v65, v9
	v_pk_add_f32 v[14:15], v[14:15], v[64:65]
	s_waitcnt vmcnt(20)
	v_mov_b32_e32 v64, v3
	v_mov_b32_e32 v65, v4
	v_mov_b32_e32 v66, v2
	v_mov_b32_e32 v67, v5
	v_pk_add_f32 v[64:65], v[64:65], v[66:67]
	v_add_f32_e32 v14, v14, v15
	v_pk_add_f32 v[64:65], v[64:65], v[64:65] op_sel_hi:[0,1]
	v_add_f32_e32 v15, 0, v14
	s_waitcnt vmcnt(19)
	v_add_f32_e32 v67, v10, v11
	v_add_f32_e32 v69, v12, v13
	s_waitcnt vmcnt(18)
	v_mov_b32_e32 v66, v16
	v_mov_b32_e32 v68, v17
	v_mov_b32_e32 v64, v18
	v_mov_b32_e32 v14, v19
	v_pk_add_f32 v[66:67], v[66:67], v[68:69]
	v_pk_add_f32 v[14:15], v[64:65], v[14:15]
	s_mov_b32 s35, s7
	v_pk_add_f32 v[14:15], v[66:67], v[14:15]
	global_load_dwordx4 v[64:67], v[62:63], off
	s_nop 0
	global_load_dwordx4 v[60:63], v[60:61], off offset:3072
	v_add_f32_e32 v14, v14, v15
	s_lshl_b64 s[10:11], s[34:35], 2
	s_add_u32 s28, s70, s10
	v_add_f32_dpp v14, v14, v14 quad_perm:[1,0,3,2] row_mask:0xf bank_mask:0xf bound_ctrl:1
	s_addc_u32 s29, s71, s11
	s_add_i32 s4, s12, 0x800
	v_add_f32_dpp v14, v14, v14 quad_perm:[2,3,0,1] row_mask:0xf bank_mask:0xf bound_ctrl:1
	s_lshr_b32 s5, s4, 11
	s_mulk_i32 s5, 0x1800
	v_add_f32_dpp v14, v14, v14 row_half_mirror row_mask:0xf bank_mask:0xf bound_ctrl:1
	s_add_i32 s6, s5, 0x1800
	s_mov_b32 s23, s7
	v_add_f32_dpp v68, v14, v14 row_mirror row_mask:0xf bank_mask:0xf bound_ctrl:1
	ds_bpermute_b32 v69, v1, v68
	v_lshl_add_u64 v[14:15], s[28:29], 0, v[94:95]
	v_lshl_add_u64 v[102:103], v[14:15], 0, s[8:9]
	v_add_co_u32_e32 v98, vcc, s0, v14
	s_waitcnt lgkmcnt(0)
	v_add_f32_e32 v68, v68, v69
	ds_bpermute_b32 v69, v96, v68
	v_addc_co_u32_e32 v99, vcc, 0, v15, vcc
	global_load_dwordx4 v[80:83], v[14:15], off
	global_load_dwordx4 v[84:87], v[14:15], off offset:1024
	s_add_i32 s28, s12, 0x1800
	s_waitcnt lgkmcnt(0)
	v_add_f32_e32 v76, v68, v69
	v_fmamk_f32 v7, v76, 0xba800000, v7
	v_fmamk_f32 v6, v76, 0xba800000, v6
	v_fmamk_f32 v9, v76, 0xba800000, v9
	v_fmac_f32_e32 v8, 0xba800000, v76
	v_pk_mul_f32 v[68:69], v[8:9], v[8:9]
	v_pk_mul_f32 v[70:71], v[6:7], v[6:7]
	v_fmamk_f32 v3, v76, 0xba800000, v3
	v_pk_mov_b32 v[72:73], v[70:71], v[68:69] op_sel:[1,0]
	v_mov_b32_e32 v71, v69
	v_pk_add_f32 v[68:69], v[72:73], v[70:71]
	v_fmamk_f32 v2, v76, 0xba800000, v2
	v_fmamk_f32 v5, v76, 0xba800000, v5
	v_fmac_f32_e32 v4, 0xba800000, v76
	v_pk_add_f32 v[68:69], v[68:69], v[68:69] op_sel_hi:[0,1]
	v_pk_mul_f32 v[70:71], v[4:5], v[4:5]
	v_pk_mul_f32 v[72:73], v[2:3], v[2:3]
	v_fmamk_f32 v10, v76, 0xba800000, v10
	v_pk_mov_b32 v[74:75], v[72:73], v[70:71] op_sel:[1,0]
	v_mov_b32_e32 v73, v71
	v_fmamk_f32 v11, v76, 0xba800000, v11
	v_fmac_f32_e32 v12, 0xba800000, v76
	v_mul_f32_e32 v68, v10, v10
	v_pk_add_f32 v[70:71], v[74:75], v[72:73]
	v_fmamk_f32 v13, v76, 0xba800000, v13
	v_pk_fma_f32 v[72:73], v[10:11], v[10:11], v[68:69] op_sel_hi:[1,1,0]
	v_mul_f32_e32 v68, v12, v12
	v_pk_add_f32 v[70:71], v[70:71], v[70:71] op_sel_hi:[0,1]
	v_pk_fma_f32 v[74:75], v[12:13], v[12:13], v[68:69] op_sel_hi:[1,1,0]
	v_fmamk_f32 v19, v76, 0xba800000, v19
	v_fmamk_f32 v18, v76, 0xba800000, v18
	v_fmamk_f32 v17, v76, 0xba800000, v17
	v_fmac_f32_e32 v16, 0xba800000, v76
	v_mul_f32_e32 v72, v16, v16
	v_mul_f32_e32 v74, v17, v17
	v_mul_f32_e32 v68, v18, v18
	v_mul_f32_e32 v70, v19, v19
	v_pk_add_f32 v[72:73], v[72:73], v[74:75]
	v_pk_add_f32 v[68:69], v[68:69], v[70:71]
	s_waitcnt vmcnt(21)
	v_mov_b32_e32 v70, v24
	v_pk_add_f32 v[68:69], v[72:73], v[68:69]
	v_mov_b32_e32 v71, v27
	v_add_f32_e32 v68, v68, v69
	v_mov_b32_e32 v69, v26
	s_waitcnt vmcnt(20)
	v_mov_b32_e32 v72, v20
	v_add_f32_dpp v68, v68, v68 quad_perm:[1,0,3,2] row_mask:0xf bank_mask:0xf bound_ctrl:1
	v_mov_b32_e32 v73, v23
	s_waitcnt vmcnt(19)
	v_add_f32_e32 v75, v34, v35
	v_add_f32_dpp v68, v68, v68 quad_perm:[2,3,0,1] row_mask:0xf bank_mask:0xf bound_ctrl:1
	s_waitcnt vmcnt(18)
	v_mov_b32_e32 v74, v29
	s_ashr_i32 s29, s28, 31
	v_add_f32_dpp v68, v68, v68 row_half_mirror row_mask:0xf bank_mask:0xf bound_ctrl:1
	s_cmpk_lt_i32 s12, 0xf800
	s_cselect_b32 s5, s29, 0
	v_add_f32_dpp v76, v68, v68 row_mirror row_mask:0xf bank_mask:0xf bound_ctrl:1
	v_mov_b32_e32 v68, v25
	v_pk_add_f32 v[68:69], v[68:69], v[70:71]
	v_mov_b32_e32 v70, v21
	v_mov_b32_e32 v71, v22
	v_pk_add_f32 v[70:71], v[70:71], v[72:73]
	v_add_f32_e32 v68, v68, v69
	v_pk_add_f32 v[70:71], v[70:71], v[70:71] op_sel_hi:[0,1]
	v_add_f32_e32 v69, 0, v68
	v_add_f32_e32 v73, v32, v33
	v_mov_b32_e32 v72, v28
	v_mov_b32_e32 v70, v30
	v_mov_b32_e32 v68, v31
	v_pk_add_f32 v[72:73], v[72:73], v[74:75]
	v_pk_add_f32 v[68:69], v[70:71], v[68:69]
	ds_bpermute_b32 v77, v1, v76
	v_pk_add_f32 v[68:69], v[72:73], v[68:69]
	s_cselect_b32 s4, s28, s4
	v_add_f32_e32 v68, v68, v69
	s_cselect_b32 s10, s57, s59
	s_waitcnt lgkmcnt(0)
	v_add_f32_e32 v100, v76, v77
	v_add_f32_dpp v68, v68, v68 quad_perm:[1,0,3,2] row_mask:0xf bank_mask:0xf bound_ctrl:1
	ds_bpermute_b32 v101, v96, v100
	s_cselect_b32 s11, s56, s58
	v_add_f32_dpp v68, v68, v68 quad_perm:[2,3,0,1] row_mask:0xf bank_mask:0xf bound_ctrl:1
	s_cselect_b32 s6, 0, s6
	s_lshl_b64 s[4:5], s[4:5], 12
	v_add_f32_dpp v68, v68, v68 row_half_mirror row_mask:0xf bank_mask:0xf bound_ctrl:1
	s_waitcnt lgkmcnt(0)
	v_add_f32_e32 v110, v100, v101
	s_add_u32 s4, s11, s4
	v_add_f32_dpp v68, v68, v68 row_mirror row_mask:0xf bank_mask:0xf bound_ctrl:1
	ds_bpermute_b32 v69, v1, v68
	s_addc_u32 s5, s10, s5
	s_waitcnt vmcnt(6)
	v_pk_add_f32 v[44:45], v[44:45], 1.0 op_sel_hi:[1,0]
	v_pk_add_f32 v[46:47], v[46:47], 1.0 op_sel_hi:[1,0]
	v_pk_add_f32 v[52:53], v[52:53], 1.0 op_sel_hi:[1,0]
	s_waitcnt lgkmcnt(0)
	v_add_f32_e32 v104, v68, v69
	ds_bpermute_b32 v105, v96, v104
	global_load_dwordx4 v[88:91], v[102:103], off offset:1024
	global_load_dwordx4 v[76:79], v[102:103], off offset:2048
	global_load_dwordx4 v[72:75], v[14:15], off offset:2048
	global_load_dwordx4 v[68:71], v[14:15], off offset:3072
	v_pk_add_f32 v[54:55], v[54:55], 1.0 op_sel_hi:[1,0]
	s_waitcnt lgkmcnt(0)
	v_add_f32_e32 v108, v104, v105
	v_fmamk_f32 v107, v108, 0xba800000, v25
	v_fmamk_f32 v106, v108, 0xba800000, v24
	v_fmamk_f32 v27, v108, 0xba800000, v27
	v_fmac_f32_e32 v26, 0xba800000, v108
	v_pk_mul_f32 v[14:15], v[26:27], v[26:27]
	v_pk_mul_f32 v[24:25], v[106:107], v[106:107]
	v_fmamk_f32 v21, v108, 0xba800000, v21
	v_pk_mov_b32 v[100:101], v[24:25], v[14:15] op_sel:[1,0]
	v_mov_b32_e32 v25, v15
	v_pk_add_f32 v[14:15], v[100:101], v[24:25]
	v_fmamk_f32 v20, v108, 0xba800000, v20
	v_fmamk_f32 v23, v108, 0xba800000, v23
	v_fmac_f32_e32 v22, 0xba800000, v108
	v_pk_add_f32 v[14:15], v[14:15], v[14:15] op_sel_hi:[0,1]
	v_pk_mul_f32 v[24:25], v[22:23], v[22:23]
	v_pk_mul_f32 v[100:101], v[20:21], v[20:21]
	v_fmamk_f32 v32, v108, 0xba800000, v32
	v_pk_mov_b32 v[104:105], v[100:101], v[24:25] op_sel:[1,0]
	v_mov_b32_e32 v101, v25
	v_fmamk_f32 v33, v108, 0xba800000, v33
	v_fmac_f32_e32 v34, 0xba800000, v108
	v_mul_f32_e32 v14, v32, v32
	v_pk_add_f32 v[24:25], v[104:105], v[100:101]
	v_fmamk_f32 v35, v108, 0xba800000, v35
	v_pk_fma_f32 v[100:101], v[32:33], v[32:33], v[14:15] op_sel_hi:[1,1,0]
	v_mul_f32_e32 v14, v34, v34
	v_pk_add_f32 v[24:25], v[24:25], v[24:25] op_sel_hi:[0,1]
	v_fmamk_f32 v31, v108, 0xba800000, v31
	v_fmamk_f32 v30, v108, 0xba800000, v30
	v_fmamk_f32 v29, v108, 0xba800000, v29
	v_fmac_f32_e32 v28, 0xba800000, v108
	v_pk_fma_f32 v[104:105], v[34:35], v[34:35], v[14:15] op_sel_hi:[1,1,0]
	v_mul_f32_e32 v100, v28, v28
	v_mul_f32_e32 v104, v29, v29
	v_mul_f32_e32 v14, v30, v30
	v_mul_f32_e32 v24, v31, v31
	v_pk_add_f32 v[108:109], v[100:101], v[104:105]
	v_pk_add_f32 v[14:15], v[14:15], v[24:25]
	v_fmamk_f32 v24, v110, 0x3a800000, v97
	v_pk_add_f32 v[14:15], v[108:109], v[14:15]
	v_rsq_f32_e32 v24, v24
	v_add_f32_e32 v14, v14, v15
	global_load_dwordx4 v[98:101], v[98:99], off
	s_nop 0
	global_load_dwordx4 v[102:105], v[102:103], off offset:3072
	v_add_f32_dpp v14, v14, v14 quad_perm:[1,0,3,2] row_mask:0xf bank_mask:0xf bound_ctrl:1
	s_nop 1
	v_add_f32_dpp v14, v14, v14 quad_perm:[2,3,0,1] row_mask:0xf bank_mask:0xf bound_ctrl:1
	s_nop 1
	v_add_f32_dpp v14, v14, v14 row_half_mirror row_mask:0xf bank_mask:0xf bound_ctrl:1
	s_nop 1
	v_add_f32_dpp v25, v14, v14 row_mirror row_mask:0xf bank_mask:0xf bound_ctrl:1
	ds_bpermute_b32 v114, v1, v25
	v_pk_mul_f32 v[112:113], v[2:3], v[24:25] op_sel_hi:[1,0]
	v_lshl_add_u64 v[14:15], s[4:5], 0, v[94:95]
	v_pk_mul_f32 v[108:109], v[8:9], v[24:25] op_sel_hi:[1,0]
	v_pk_mul_f32 v[110:111], v[6:7], v[24:25] op_sel_hi:[1,0]
	s_waitcnt lgkmcnt(0)
	v_add_f32_e32 v2, v25, v114
	ds_bpermute_b32 v3, v96, v2
	v_pk_mul_f32 v[114:115], v[4:5], v[24:25] op_sel_hi:[1,0]
	v_pk_mul_f32 v[116:117], v[10:11], v[24:25] op_sel_hi:[1,0]
	v_pk_mul_f32 v[118:119], v[12:13], v[24:25] op_sel_hi:[1,0]
	v_pk_mul_f32 v[120:121], v[16:17], v[24:25] op_sel_hi:[1,0]
	s_waitcnt lgkmcnt(0)
	v_add_f32_e32 v2, v2, v3
	v_fmamk_f32 v2, v2, 0x3a800000, v97
	v_rsq_f32_e32 v122, v2
	global_load_dwordx4 v[6:9], v[14:15], off
	global_load_dwordx4 v[2:5], v[14:15], off offset:1024
	global_load_dwordx4 v[10:13], v[14:15], off offset:2048
	s_nop 0
	global_load_dwordx4 v[14:17], v[14:15], off offset:3072
	s_lshl_b64 s[4:5], s[26:27], 12
	s_add_u32 s4, s3, s4
	s_addc_u32 s5, s1, s5
	v_pk_mul_f32 v[128:129], v[22:23], v[122:123] op_sel_hi:[1,0]
	s_waitcnt vmcnt(13)
	v_pk_add_f32 v[22:23], v[64:65], 1.0 op_sel_hi:[1,0]
	v_lshl_add_u64 v[64:65], s[4:5], 0, v[94:95]
	v_pk_mul_f32 v[124:125], v[18:19], v[24:25] op_sel_hi:[1,0]
	v_pk_mul_f32 v[126:127], v[26:27], v[122:123] op_sel_hi:[1,0]
	v_pk_mul_f32 v[130:131], v[28:29], v[122:123] op_sel_hi:[1,0]
	v_pk_fma_f32 v[56:57], v[22:23], v[110:111], v[56:57]
	global_load_dwordx4 v[26:29], v[64:65], off
	global_load_dwordx4 v[22:25], v[64:65], off offset:1024
	v_pk_add_f32 v[18:19], v[66:67], 1.0 op_sel_hi:[1,0]
	v_pk_mul_f32 v[66:67], v[20:21], v[122:123] op_sel_hi:[1,0]
	v_pk_fma_f32 v[18:19], v[18:19], v[108:109], v[58:59]
	v_pk_mul_f32 v[58:59], v[106:107], v[122:123] op_sel_hi:[1,0]
	v_pk_mul_f32 v[106:107], v[32:33], v[122:123] op_sel_hi:[1,0]
	v_pk_mul_f32 v[108:109], v[30:31], v[122:123] op_sel_hi:[1,0]
	v_cvt_pk_bf16_f32 v56, v56, v57
	v_cvt_pk_bf16_f32 v57, v18, v19
	global_load_dwordx4 v[30:33], v[64:65], off offset:2048
	global_load_dwordx4 v[18:21], v[64:65], off offset:3072
	s_lshl_b64 s[4:5], s[30:31], 11
	v_pk_fma_f32 v[40:41], v[44:45], v[116:117], v[40:41]
	v_lshl_add_u64 v[64:65], v[92:93], 0, s[4:5]
	v_pk_fma_f32 v[42:43], v[46:47], v[118:119], v[42:43]
	v_cvt_pk_bf16_f32 v40, v40, v41
	s_lshl_b64 s[4:5], s[24:25], 11
	v_cvt_pk_bf16_f32 v41, v42, v43
	global_store_dwordx2 v[64:65], v[40:41], off offset:1024
	s_waitcnt vmcnt(17)
	v_pk_add_f32 v[40:41], v[62:63], 1.0 op_sel_hi:[1,0]
	v_pk_add_f32 v[42:43], v[60:61], 1.0 op_sel_hi:[1,0]
	v_pk_fma_f32 v[38:39], v[40:41], v[124:125], v[38:39]
	v_pk_fma_f32 v[36:37], v[42:43], v[120:121], v[36:37]
	v_pk_fma_f32 v[48:49], v[52:53], v[112:113], v[48:49]
	v_cvt_pk_bf16_f32 v36, v36, v37
	v_cvt_pk_bf16_f32 v37, v38, v39
	global_store_dwordx2 v[64:65], v[36:37], off offset:1536
	v_lshl_add_u64 v[36:37], v[92:93], 0, s[4:5]
	v_pk_mul_f32 v[34:35], v[34:35], v[122:123] op_sel_hi:[1,0]
	global_store_dwordx2 v[64:65], v[56:57], off
	v_pk_fma_f32 v[50:51], v[54:55], v[114:115], v[50:51]
	v_cvt_pk_bf16_f32 v48, v48, v49
	s_lshl_b64 s[4:5], s[6:7], 2
	v_cvt_pk_bf16_f32 v49, v50, v51
	global_store_dwordx2 v[64:65], v[48:49], off offset:512
	s_add_u32 s4, s70, s4
	s_addc_u32 s5, s71, s5
	s_lshl_b64 s[10:11], s[22:23], 2
	s_add_u32 s22, s70, s10
	s_addc_u32 s23, s71, s11
	s_add_i32 s1, s12, 0x1400
	s_lshr_b32 s3, s1, 11
	s_add_i32 s24, s12, 0x2400
	s_waitcnt vmcnt(13)
	v_pk_add_f32 v[40:41], v[98:99], 1.0 op_sel_hi:[1,0]
	v_pk_add_f32 v[38:39], v[100:101], 1.0 op_sel_hi:[1,0]
	v_pk_fma_f32 v[40:41], v[40:41], v[58:59], v[80:81]
	v_pk_fma_f32 v[38:39], v[38:39], v[126:127], v[82:83]
	v_cvt_pk_bf16_f32 v40, v40, v41
	s_mulk_i32 s3, 0x1800
	v_cvt_pk_bf16_f32 v41, v38, v39
	global_store_dwordx2 v[36:37], v[40:41], off
	v_pk_add_f32 v[40:41], v[88:89], 1.0 op_sel_hi:[1,0]
	v_pk_add_f32 v[38:39], v[90:91], 1.0 op_sel_hi:[1,0]
	v_pk_fma_f32 v[40:41], v[40:41], v[66:67], v[84:85]
	v_pk_fma_f32 v[38:39], v[38:39], v[128:129], v[86:87]
	v_cvt_pk_bf16_f32 v40, v40, v41
	s_ashr_i32 s25, s24, 31
	v_cvt_pk_bf16_f32 v41, v38, v39
	global_store_dwordx2 v[36:37], v[40:41], off offset:512
	v_pk_add_f32 v[38:39], v[78:79], 1.0 op_sel_hi:[1,0]
	v_pk_add_f32 v[40:41], v[76:77], 1.0 op_sel_hi:[1,0]
	v_pk_fma_f32 v[34:35], v[38:39], v[34:35], v[74:75]
	v_pk_fma_f32 v[38:39], v[40:41], v[106:107], v[72:73]
	s_addk_i32 s3, 0x1800
	v_cvt_pk_bf16_f32 v38, v38, v39
	v_cvt_pk_bf16_f32 v39, v34, v35
	global_store_dwordx2 v[36:37], v[38:39], off offset:1024
	s_waitcnt vmcnt(15)
	v_pk_add_f32 v[38:39], v[102:103], 1.0 op_sel_hi:[1,0]
	s_waitcnt vmcnt(14)
	v_mov_b32_e32 v62, v7
	v_mov_b32_e32 v63, v8
	v_mov_b32_e32 v64, v6
	v_mov_b32_e32 v65, v9
	v_pk_add_f32 v[62:63], v[62:63], v[64:65]
	s_waitcnt vmcnt(13)
	v_mov_b32_e32 v64, v3
	v_mov_b32_e32 v65, v4
	v_mov_b32_e32 v66, v2
	v_mov_b32_e32 v67, v5
	v_pk_add_f32 v[64:65], v[64:65], v[66:67]
	v_add_f32_e32 v62, v62, v63
	v_pk_add_f32 v[64:65], v[64:65], v[64:65] op_sel_hi:[0,1]
	v_pk_fma_f32 v[38:39], v[38:39], v[130:131], v[68:69]
	v_add_f32_e32 v63, 0, v62
	s_waitcnt vmcnt(12)
	v_add_f32_e32 v67, v10, v11
	v_add_f32_e32 v69, v12, v13
	s_waitcnt vmcnt(11)
	v_mov_b32_e32 v66, v14
	v_mov_b32_e32 v68, v15
	v_mov_b32_e32 v64, v16
	v_mov_b32_e32 v62, v17
	v_pk_add_f32 v[66:67], v[66:67], v[68:69]
	v_pk_add_f32 v[62:63], v[64:65], v[62:63]
	v_pk_add_f32 v[34:35], v[104:105], 1.0 op_sel_hi:[1,0]
	v_pk_add_f32 v[62:63], v[66:67], v[62:63]
	v_pk_fma_f32 v[34:35], v[34:35], v[108:109], v[70:71]
	v_add_f32_e32 v62, v62, v63
	v_cvt_pk_bf16_f32 v38, v38, v39
	v_cvt_pk_bf16_f32 v39, v34, v35
	v_lshl_add_u64 v[34:35], s[4:5], 0, v[94:95]
	v_add_co_u32_e32 v60, vcc, s0, v34
	v_add_f32_dpp v62, v62, v62 quad_perm:[1,0,3,2] row_mask:0xf bank_mask:0xf bound_ctrl:1
	global_store_dwordx2 v[36:37], v[38:39], off offset:1536
	v_lshl_add_u64 v[58:59], v[34:35], 0, s[8:9]
	v_add_f32_dpp v62, v62, v62 quad_perm:[2,3,0,1] row_mask:0xf bank_mask:0xf bound_ctrl:1
	v_addc_co_u32_e32 v61, vcc, 0, v35, vcc
	s_nop 0
	v_add_f32_dpp v62, v62, v62 row_half_mirror row_mask:0xf bank_mask:0xf bound_ctrl:1
	global_load_dwordx4 v[54:57], v[34:35], off
	global_load_dwordx4 v[46:49], v[34:35], off offset:1024
	global_load_dwordx4 v[50:53], v[58:59], off offset:1024
	global_load_dwordx4 v[42:45], v[58:59], off offset:2048
	global_load_dwordx4 v[38:41], v[34:35], off offset:2048
	s_nop 0
	global_load_dwordx4 v[34:37], v[34:35], off offset:3072
	v_add_f32_dpp v68, v62, v62 row_mirror row_mask:0xf bank_mask:0xf bound_ctrl:1
	ds_bpermute_b32 v69, v1, v68
	global_load_dwordx4 v[62:65], v[60:61], off
	s_nop 0
	global_load_dwordx4 v[58:61], v[58:59], off offset:3072
	v_lshl_add_u64 v[66:67], s[22:23], 0, v[94:95]
	v_add_co_u32_e32 v98, vcc, s0, v66
	s_waitcnt lgkmcnt(0)
	v_add_f32_e32 v68, v68, v69
	ds_bpermute_b32 v69, v96, v68
	v_lshl_add_u64 v[90:91], v[66:67], 0, s[8:9]
	v_addc_co_u32_e32 v99, vcc, 0, v67, vcc
	global_load_dwordx4 v[82:85], v[66:67], off
	global_load_dwordx4 v[78:81], v[66:67], off offset:1024
	s_waitcnt lgkmcnt(0)
	v_add_f32_e32 v76, v68, v69
	v_fmamk_f32 v7, v76, 0xba800000, v7
	v_fmamk_f32 v6, v76, 0xba800000, v6
	v_fmamk_f32 v9, v76, 0xba800000, v9
	v_fmac_f32_e32 v8, 0xba800000, v76
	v_pk_mul_f32 v[68:69], v[8:9], v[8:9]
	v_pk_mul_f32 v[70:71], v[6:7], v[6:7]
	v_fmamk_f32 v3, v76, 0xba800000, v3
	v_pk_mov_b32 v[72:73], v[70:71], v[68:69] op_sel:[1,0]
	v_mov_b32_e32 v71, v69
	v_pk_add_f32 v[68:69], v[72:73], v[70:71]
	v_fmamk_f32 v2, v76, 0xba800000, v2
	v_fmamk_f32 v5, v76, 0xba800000, v5
	v_fmac_f32_e32 v4, 0xba800000, v76
	v_pk_add_f32 v[68:69], v[68:69], v[68:69] op_sel_hi:[0,1]
	v_pk_mul_f32 v[70:71], v[4:5], v[4:5]
	v_pk_mul_f32 v[72:73], v[2:3], v[2:3]
	v_fmamk_f32 v10, v76, 0xba800000, v10
	v_pk_mov_b32 v[74:75], v[72:73], v[70:71] op_sel:[1,0]
	v_mov_b32_e32 v73, v71
	v_fmamk_f32 v11, v76, 0xba800000, v11
	v_fmac_f32_e32 v12, 0xba800000, v76
	v_mul_f32_e32 v68, v10, v10
	v_pk_add_f32 v[70:71], v[74:75], v[72:73]
	v_fmamk_f32 v13, v76, 0xba800000, v13
	v_pk_fma_f32 v[72:73], v[10:11], v[10:11], v[68:69] op_sel_hi:[1,1,0]
	v_mul_f32_e32 v68, v12, v12
	v_pk_add_f32 v[70:71], v[70:71], v[70:71] op_sel_hi:[0,1]
	v_pk_fma_f32 v[74:75], v[12:13], v[12:13], v[68:69] op_sel_hi:[1,1,0]
	v_fmamk_f32 v17, v76, 0xba800000, v17
	v_fmamk_f32 v16, v76, 0xba800000, v16
	v_fmamk_f32 v15, v76, 0xba800000, v15
	v_fmac_f32_e32 v14, 0xba800000, v76
	v_mul_f32_e32 v72, v14, v14
	v_mul_f32_e32 v74, v15, v15
	v_mul_f32_e32 v68, v16, v16
	v_mul_f32_e32 v70, v17, v17
	v_pk_add_f32 v[72:73], v[72:73], v[74:75]
	v_pk_add_f32 v[68:69], v[68:69], v[70:71]
	s_waitcnt vmcnt(21)
	v_mov_b32_e32 v70, v26
	v_pk_add_f32 v[68:69], v[72:73], v[68:69]
	v_mov_b32_e32 v71, v29
	v_add_f32_e32 v68, v68, v69
	v_mov_b32_e32 v69, v28
	s_waitcnt vmcnt(20)
	v_mov_b32_e32 v72, v22
	v_add_f32_dpp v68, v68, v68 quad_perm:[1,0,3,2] row_mask:0xf bank_mask:0xf bound_ctrl:1
	v_mov_b32_e32 v73, v25
	s_waitcnt vmcnt(19)
	v_add_f32_e32 v75, v32, v33
	v_add_f32_dpp v68, v68, v68 quad_perm:[2,3,0,1] row_mask:0xf bank_mask:0xf bound_ctrl:1
	s_waitcnt vmcnt(18)
	v_mov_b32_e32 v74, v19
	s_cmpk_lt_i32 s12, 0xec00
	v_add_f32_dpp v68, v68, v68 row_half_mirror row_mask:0xf bank_mask:0xf bound_ctrl:1
	s_cselect_b32 s5, s25, 0
	s_cselect_b32 s4, s24, s1
	v_add_f32_dpp v76, v68, v68 row_mirror row_mask:0xf bank_mask:0xf bound_ctrl:1
	v_mov_b32_e32 v68, v27
	v_pk_add_f32 v[68:69], v[68:69], v[70:71]
	v_mov_b32_e32 v70, v23
	v_mov_b32_e32 v71, v24
	v_pk_add_f32 v[70:71], v[70:71], v[72:73]
	v_add_f32_e32 v68, v68, v69
	v_pk_add_f32 v[70:71], v[70:71], v[70:71] op_sel_hi:[0,1]
	v_add_f32_e32 v69, 0, v68
	v_add_f32_e32 v73, v30, v31
	v_mov_b32_e32 v72, v18
	v_mov_b32_e32 v70, v20
	v_mov_b32_e32 v68, v21
	v_pk_add_f32 v[72:73], v[72:73], v[74:75]
	v_pk_add_f32 v[68:69], v[70:71], v[68:69]
	ds_bpermute_b32 v77, v1, v76
	v_pk_add_f32 v[68:69], v[72:73], v[68:69]
	s_cselect_b32 s1, s57, s59
	v_add_f32_e32 v68, v68, v69
	s_cselect_b32 s6, s56, s58
	s_waitcnt lgkmcnt(0)
	v_add_f32_e32 v100, v76, v77
	v_add_f32_dpp v68, v68, v68 quad_perm:[1,0,3,2] row_mask:0xf bank_mask:0xf bound_ctrl:1
	ds_bpermute_b32 v101, v96, v100
	s_cselect_b32 s26, 0, s3
	v_add_f32_dpp v68, v68, v68 quad_perm:[2,3,0,1] row_mask:0xf bank_mask:0xf bound_ctrl:1
	s_lshl_b64 s[4:5], s[4:5], 12
	s_add_u32 s4, s6, s4
	v_add_f32_dpp v68, v68, v68 row_half_mirror row_mask:0xf bank_mask:0xf bound_ctrl:1
	s_waitcnt lgkmcnt(0)
	v_add_f32_e32 v110, v100, v101
	s_addc_u32 s5, s1, s5
	v_add_f32_dpp v68, v68, v68 row_mirror row_mask:0xf bank_mask:0xf bound_ctrl:1
	ds_bpermute_b32 v69, v1, v68
	s_add_i32 s1, s12, 0x1a00
	s_lshr_b32 s3, s1, 11
	s_add_i32 s22, s12, 0x2a00
	s_mulk_i32 s3, 0x1800
	s_waitcnt lgkmcnt(0)
	v_add_f32_e32 v102, v68, v69
	ds_bpermute_b32 v103, v96, v102
	global_load_dwordx4 v[86:89], v[90:91], off offset:1024
	global_load_dwordx4 v[74:77], v[90:91], off offset:2048
	global_load_dwordx4 v[70:73], v[66:67], off offset:2048
	s_nop 0
	global_load_dwordx4 v[66:69], v[66:67], off offset:3072
	s_ashr_i32 s23, s22, 31
	s_addk_i32 s3, 0x1800
	s_cmpk_lt_i32 s12, 0xe600
	s_waitcnt lgkmcnt(0)
	v_add_f32_e32 v111, v102, v103
	v_fmamk_f32 v27, v111, 0xba800000, v27
	v_fmamk_f32 v26, v111, 0xba800000, v26
	v_fmamk_f32 v29, v111, 0xba800000, v29
	v_fmac_f32_e32 v28, 0xba800000, v111
	v_pk_mul_f32 v[100:101], v[28:29], v[28:29]
	v_pk_mul_f32 v[102:103], v[26:27], v[26:27]
	v_fmamk_f32 v107, v111, 0xba800000, v23
	v_pk_mov_b32 v[104:105], v[102:103], v[100:101] op_sel:[1,0]
	v_mov_b32_e32 v103, v101
	v_fmamk_f32 v106, v111, 0xba800000, v22
	v_fmamk_f32 v25, v111, 0xba800000, v25
	v_fmac_f32_e32 v24, 0xba800000, v111
	v_pk_add_f32 v[100:101], v[104:105], v[102:103]
	v_pk_mul_f32 v[22:23], v[24:25], v[24:25]
	v_pk_mul_f32 v[102:103], v[106:107], v[106:107]
	v_fmamk_f32 v30, v111, 0xba800000, v30
	v_pk_mov_b32 v[104:105], v[102:103], v[22:23] op_sel:[1,0]
	v_mov_b32_e32 v103, v23
	v_pk_add_f32 v[22:23], v[104:105], v[102:103]
	v_fmac_f32_e32 v32, 0xba800000, v111
	v_pk_add_f32 v[22:23], v[22:23], v[22:23] op_sel_hi:[0,1]
	v_fmamk_f32 v31, v111, 0xba800000, v31
	v_fmamk_f32 v33, v111, 0xba800000, v33
	v_mul_f32_e32 v22, v30, v30
	v_fmamk_f32 v108, v111, 0xba800000, v20
	v_mul_f32_e32 v20, v32, v32
	v_pk_add_f32 v[100:101], v[100:101], v[100:101] op_sel_hi:[0,1]
	v_pk_fma_f32 v[102:103], v[30:31], v[30:31], v[22:23] op_sel_hi:[1,1,0]
	v_fmamk_f32 v109, v111, 0xba800000, v21
	v_fmamk_f32 v19, v111, 0xba800000, v19
	v_fmac_f32_e32 v18, 0xba800000, v111
	v_pk_fma_f32 v[20:21], v[32:33], v[32:33], v[20:21] op_sel_hi:[1,1,0]
	v_mul_f32_e32 v102, v18, v18
	v_mul_f32_e32 v20, v19, v19
	v_mul_f32_e32 v100, v108, v108
	v_mul_f32_e32 v22, v109, v109
	v_pk_add_f32 v[20:21], v[102:103], v[20:21]
	v_pk_add_f32 v[22:23], v[100:101], v[22:23]
	global_load_dwordx4 v[98:101], v[98:99], off
	s_nop 0
	global_load_dwordx4 v[102:105], v[90:91], off offset:3072
	v_pk_add_f32 v[20:21], v[20:21], v[22:23]
	v_fmamk_f32 v90, v110, 0x3a800000, v97
	v_add_f32_e32 v20, v20, v21
	v_rsq_f32_e32 v22, v90
	v_lshl_add_u64 v[90:91], s[4:5], 0, v[94:95]
	v_add_f32_dpp v20, v20, v20 quad_perm:[1,0,3,2] row_mask:0xf bank_mask:0xf bound_ctrl:1
	s_cselect_b32 s5, s23, 0
	s_cselect_b32 s4, s22, s1
	v_add_f32_dpp v20, v20, v20 quad_perm:[2,3,0,1] row_mask:0xf bank_mask:0xf bound_ctrl:1
	s_cselect_b32 s1, s57, s59
	s_cselect_b32 s10, s56, s58
	v_add_f32_dpp v20, v20, v20 row_half_mirror row_mask:0xf bank_mask:0xf bound_ctrl:1
	s_cselect_b32 s6, 0, s3
	s_lshl_b64 s[4:5], s[4:5], 12
	v_add_f32_dpp v23, v20, v20 row_mirror row_mask:0xf bank_mask:0xf bound_ctrl:1
	ds_bpermute_b32 v114, v1, v23
	v_pk_mul_f32 v[112:113], v[2:3], v[22:23] op_sel_hi:[1,0]
	v_pk_mul_f32 v[20:21], v[8:9], v[22:23] op_sel_hi:[1,0]
	v_pk_mul_f32 v[110:111], v[6:7], v[22:23] op_sel_hi:[1,0]
	v_pk_mul_f32 v[116:117], v[10:11], v[22:23] op_sel_hi:[1,0]
	s_waitcnt lgkmcnt(0)
	v_add_f32_e32 v2, v23, v114
	ds_bpermute_b32 v3, v96, v2
	v_pk_mul_f32 v[114:115], v[4:5], v[22:23] op_sel_hi:[1,0]
	v_pk_mul_f32 v[118:119], v[12:13], v[22:23] op_sel_hi:[1,0]
	v_pk_mul_f32 v[120:121], v[14:15], v[22:23] op_sel_hi:[1,0]
	v_pk_mul_f32 v[124:125], v[16:17], v[22:23] op_sel_hi:[1,0]
	s_waitcnt lgkmcnt(0)
	v_add_f32_e32 v2, v2, v3
	v_fmamk_f32 v2, v2, 0x3a800000, v97
	v_rsq_f32_e32 v122, v2
	global_load_dwordx4 v[6:9], v[90:91], off
	global_load_dwordx4 v[2:5], v[90:91], off offset:1024
	global_load_dwordx4 v[10:13], v[90:91], off offset:2048
	global_load_dwordx4 v[14:17], v[90:91], off offset:3072
	s_add_u32 s4, s10, s4
	s_addc_u32 s5, s1, s5
	v_pk_mul_f32 v[126:127], v[28:29], v[122:123] op_sel_hi:[1,0]
	v_pk_mul_f32 v[90:91], v[18:19], v[122:123] op_sel_hi:[1,0]
	s_waitcnt vmcnt(13)
	v_pk_add_f32 v[18:19], v[64:65], 1.0 op_sel_hi:[1,0]
	v_pk_add_f32 v[22:23], v[62:63], 1.0 op_sel_hi:[1,0]
	v_lshl_add_u64 v[28:29], s[4:5], 0, v[94:95]
	v_pk_mul_f32 v[128:129], v[24:25], v[122:123] op_sel_hi:[1,0]
	v_pk_mul_f32 v[130:131], v[32:33], v[122:123] op_sel_hi:[1,0]
	v_pk_fma_f32 v[32:33], v[18:19], v[20:21], v[56:57]
	v_pk_fma_f32 v[54:55], v[22:23], v[110:111], v[54:55]
	global_load_dwordx4 v[22:25], v[28:29], off
	global_load_dwordx4 v[18:21], v[28:29], off offset:1024
	v_pk_mul_f32 v[56:57], v[26:27], v[122:123] op_sel_hi:[1,0]
	v_pk_mul_f32 v[64:65], v[30:31], v[122:123] op_sel_hi:[1,0]
	v_cvt_pk_bf16_f32 v54, v54, v55
	v_cvt_pk_bf16_f32 v55, v32, v33
	global_load_dwordx4 v[30:33], v[28:29], off offset:2048
	s_nop 0
	global_load_dwordx4 v[26:29], v[28:29], off offset:3072
	v_pk_add_f32 v[42:43], v[42:43], 1.0 op_sel_hi:[1,0]
	s_lshl_b64 s[4:5], s[28:29], 11
	v_pk_add_f32 v[44:45], v[44:45], 1.0 op_sel_hi:[1,0]
	v_pk_fma_f32 v[38:39], v[42:43], v[116:117], v[38:39]
	v_pk_mul_f32 v[62:63], v[106:107], v[122:123] op_sel_hi:[1,0]
	v_pk_mul_f32 v[106:107], v[108:109], v[122:123] op_sel_hi:[1,0]
	v_lshl_add_u64 v[108:109], v[92:93], 0, s[4:5]
	v_pk_fma_f32 v[40:41], v[44:45], v[118:119], v[40:41]
	v_cvt_pk_bf16_f32 v38, v38, v39
	s_lshl_b64 s[4:5], s[20:21], 11
	v_cvt_pk_bf16_f32 v39, v40, v41
	global_store_dwordx2 v[108:109], v[38:39], off offset:1024
	s_waitcnt vmcnt(17)
	v_pk_add_f32 v[38:39], v[60:61], 1.0 op_sel_hi:[1,0]
	v_pk_add_f32 v[40:41], v[58:59], 1.0 op_sel_hi:[1,0]
	v_pk_fma_f32 v[36:37], v[38:39], v[124:125], v[36:37]
	v_pk_fma_f32 v[34:35], v[40:41], v[120:121], v[34:35]
	s_mov_b32 s27, s7
	v_cvt_pk_bf16_f32 v34, v34, v35
	v_cvt_pk_bf16_f32 v35, v36, v37
	global_store_dwordx2 v[108:109], v[34:35], off offset:1536
	v_lshl_add_u64 v[34:35], v[92:93], 0, s[4:5]
	s_lshl_b64 s[4:5], s[6:7], 2
	s_add_u32 s4, s70, s4
	s_addc_u32 s5, s71, s5
	v_pk_add_f32 v[50:51], v[50:51], 1.0 op_sel_hi:[1,0]
	v_pk_add_f32 v[52:53], v[52:53], 1.0 op_sel_hi:[1,0]
	v_pk_fma_f32 v[46:47], v[50:51], v[112:113], v[46:47]
	v_pk_fma_f32 v[48:49], v[52:53], v[114:115], v[48:49]
	v_cvt_pk_bf16_f32 v46, v46, v47
	global_store_dwordx2 v[108:109], v[54:55], off
	s_waitcnt vmcnt(12)
	v_pk_add_f32 v[38:39], v[98:99], 1.0 op_sel_hi:[1,0]
	v_pk_add_f32 v[36:37], v[100:101], 1.0 op_sel_hi:[1,0]
	v_pk_fma_f32 v[38:39], v[38:39], v[56:57], v[82:83]
	v_pk_fma_f32 v[36:37], v[36:37], v[126:127], v[84:85]
	v_cvt_pk_bf16_f32 v38, v38, v39
	v_cvt_pk_bf16_f32 v47, v48, v49
	global_store_dwordx2 v[108:109], v[46:47], off offset:512
	v_cvt_pk_bf16_f32 v39, v36, v37
	global_store_dwordx2 v[34:35], v[38:39], off
	v_pk_add_f32 v[38:39], v[86:87], 1.0 op_sel_hi:[1,0]
	v_pk_add_f32 v[36:37], v[88:89], 1.0 op_sel_hi:[1,0]
	v_pk_fma_f32 v[38:39], v[38:39], v[62:63], v[78:79]
	v_pk_fma_f32 v[36:37], v[36:37], v[128:129], v[80:81]
	v_cvt_pk_bf16_f32 v38, v38, v39
	s_waitcnt vmcnt(12)
	v_mov_b32_e32 v58, v7
	v_mov_b32_e32 v59, v8
	v_mov_b32_e32 v60, v6
	v_mov_b32_e32 v61, v9
	v_pk_add_f32 v[58:59], v[58:59], v[60:61]
	s_waitcnt vmcnt(11)
	v_mov_b32_e32 v60, v3
	v_mov_b32_e32 v61, v4
	v_mov_b32_e32 v62, v2
	v_mov_b32_e32 v63, v5
	v_cvt_pk_bf16_f32 v39, v36, v37
	v_pk_add_f32 v[60:61], v[60:61], v[62:63]
	global_store_dwordx2 v[34:35], v[38:39], off offset:512
	v_pk_add_f32 v[38:39], v[74:75], 1.0 op_sel_hi:[1,0]
	v_add_f32_e32 v58, v58, v59
	v_pk_add_f32 v[60:61], v[60:61], v[60:61] op_sel_hi:[0,1]
	v_pk_fma_f32 v[38:39], v[38:39], v[64:65], v[70:71]
	v_add_f32_e32 v59, 0, v58
	s_waitcnt vmcnt(11)
	v_add_f32_e32 v63, v10, v11
	v_add_f32_e32 v65, v12, v13
	s_waitcnt vmcnt(10)
	v_mov_b32_e32 v62, v14
	v_mov_b32_e32 v64, v15
	v_mov_b32_e32 v60, v16
	v_mov_b32_e32 v58, v17
	v_pk_add_f32 v[62:63], v[62:63], v[64:65]
	v_pk_add_f32 v[58:59], v[60:61], v[58:59]
	v_lshl_add_u64 v[74:75], s[4:5], 0, v[94:95]
	v_pk_add_f32 v[58:59], v[62:63], v[58:59]
	s_lshl_b64 s[4:5], s[26:27], 2
	v_add_f32_e32 v58, v58, v59
	s_add_u32 s4, s70, s4
	s_addc_u32 s5, s71, s5
	v_add_f32_dpp v58, v58, v58 quad_perm:[1,0,3,2] row_mask:0xf bank_mask:0xf bound_ctrl:1
	v_lshl_add_u64 v[88:89], s[4:5], 0, v[94:95]
	v_pk_add_f32 v[36:37], v[76:77], 1.0 op_sel_hi:[1,0]
	v_add_f32_dpp v58, v58, v58 quad_perm:[2,3,0,1] row_mask:0xf bank_mask:0xf bound_ctrl:1
	v_pk_fma_f32 v[36:37], v[36:37], v[130:131], v[72:73]
	v_cvt_pk_bf16_f32 v38, v38, v39
	v_add_co_u32_e32 v46, vcc, s0, v74
	v_add_f32_dpp v58, v58, v58 row_half_mirror row_mask:0xf bank_mask:0xf bound_ctrl:1
	v_cvt_pk_bf16_f32 v39, v36, v37
	global_store_dwordx2 v[34:35], v[38:39], off offset:1024
	v_pk_add_f32 v[38:39], v[102:103], 1.0 op_sel_hi:[1,0]
	v_add_f32_dpp v58, v58, v58 row_mirror row_mask:0xf bank_mask:0xf bound_ctrl:1
	ds_bpermute_b32 v59, v1, v58
	v_pk_add_f32 v[36:37], v[104:105], 1.0 op_sel_hi:[1,0]
	v_pk_fma_f32 v[38:39], v[38:39], v[90:91], v[66:67]
	v_addc_co_u32_e32 v47, vcc, 0, v75, vcc
	s_waitcnt lgkmcnt(0)
	v_add_f32_e32 v78, v58, v59
	ds_bpermute_b32 v79, v96, v78
	v_pk_fma_f32 v[36:37], v[36:37], v[106:107], v[68:69]
	v_cvt_pk_bf16_f32 v38, v38, v39
	v_lshl_add_u64 v[76:77], v[88:89], 0, s[8:9]
	v_cvt_pk_bf16_f32 v39, v36, v37
	s_waitcnt lgkmcnt(0)
	v_add_f32_e32 v86, v78, v79
	v_fmamk_f32 v7, v86, 0xba800000, v7
	v_fmamk_f32 v6, v86, 0xba800000, v6
	v_fmamk_f32 v9, v86, 0xba800000, v9
	v_fmac_f32_e32 v8, 0xba800000, v86
	v_pk_mul_f32 v[78:79], v[8:9], v[8:9]
	v_pk_mul_f32 v[80:81], v[6:7], v[6:7]
	v_fmamk_f32 v3, v86, 0xba800000, v3
	v_pk_mov_b32 v[82:83], v[80:81], v[78:79] op_sel:[1,0]
	v_mov_b32_e32 v81, v79
	v_pk_add_f32 v[78:79], v[82:83], v[80:81]
	v_fmamk_f32 v2, v86, 0xba800000, v2
	v_fmamk_f32 v5, v86, 0xba800000, v5
	v_fmac_f32_e32 v4, 0xba800000, v86
	v_pk_add_f32 v[78:79], v[78:79], v[78:79] op_sel_hi:[0,1]
	v_pk_mul_f32 v[80:81], v[4:5], v[4:5]
	v_pk_mul_f32 v[82:83], v[2:3], v[2:3]
	v_fmamk_f32 v10, v86, 0xba800000, v10
	v_pk_mov_b32 v[84:85], v[82:83], v[80:81] op_sel:[1,0]
	v_mov_b32_e32 v83, v81
	v_fmamk_f32 v11, v86, 0xba800000, v11
	v_fmac_f32_e32 v12, 0xba800000, v86
	v_mul_f32_e32 v78, v10, v10
	v_pk_add_f32 v[80:81], v[84:85], v[82:83]
	v_fmamk_f32 v13, v86, 0xba800000, v13
	v_pk_fma_f32 v[82:83], v[10:11], v[10:11], v[78:79] op_sel_hi:[1,1,0]
	v_mul_f32_e32 v78, v12, v12
	v_pk_add_f32 v[80:81], v[80:81], v[80:81] op_sel_hi:[0,1]
	v_pk_fma_f32 v[84:85], v[12:13], v[12:13], v[78:79] op_sel_hi:[1,1,0]
	v_fmamk_f32 v95, v86, 0xba800000, v17
	v_fmamk_f32 v94, v86, 0xba800000, v16
	v_fmamk_f32 v15, v86, 0xba800000, v15
	v_fmac_f32_e32 v14, 0xba800000, v86
	v_mul_f32_e32 v82, v14, v14
	v_mul_f32_e32 v84, v15, v15
	v_mul_f32_e32 v78, v94, v94
	v_mul_f32_e32 v80, v95, v95
	v_pk_add_f32 v[16:17], v[82:83], v[84:85]
	v_pk_add_f32 v[78:79], v[78:79], v[80:81]
	s_waitcnt vmcnt(9)
	v_mov_b32_e32 v80, v18
	v_pk_add_f32 v[16:17], v[16:17], v[78:79]
	v_mov_b32_e32 v78, v22
	v_add_f32_e32 v16, v16, v17
	v_mov_b32_e32 v17, v24
	v_mov_b32_e32 v79, v25
	v_add_f32_dpp v16, v16, v16 quad_perm:[1,0,3,2] row_mask:0xf bank_mask:0xf bound_ctrl:1
	v_mov_b32_e32 v81, v21
	s_waitcnt vmcnt(8)
	v_add_f32_e32 v83, v32, v33
	v_add_f32_dpp v16, v16, v16 quad_perm:[2,3,0,1] row_mask:0xf bank_mask:0xf bound_ctrl:1
	s_waitcnt vmcnt(7)
	v_mov_b32_e32 v82, v27
	global_store_dwordx2 v[34:35], v[38:39], off offset:1536
	v_add_f32_dpp v16, v16, v16 row_half_mirror row_mask:0xf bank_mask:0xf bound_ctrl:1
	v_lshl_add_u64 v[34:35], v[74:75], 0, s[8:9]
	global_load_dwordx4 v[38:41], v[34:35], off offset:2048
	global_load_dwordx4 v[42:45], v[34:35], off offset:1024
	v_add_f32_dpp v84, v16, v16 row_mirror row_mask:0xf bank_mask:0xf bound_ctrl:1
	v_mov_b32_e32 v16, v23
	v_pk_add_f32 v[16:17], v[16:17], v[78:79]
	v_mov_b32_e32 v78, v19
	v_mov_b32_e32 v79, v20
	v_pk_add_f32 v[78:79], v[78:79], v[80:81]
	v_add_f32_e32 v16, v16, v17
	v_pk_add_f32 v[78:79], v[78:79], v[78:79] op_sel_hi:[0,1]
	v_add_f32_e32 v17, 0, v16
	v_add_f32_e32 v81, v30, v31
	v_mov_b32_e32 v80, v26
	v_mov_b32_e32 v78, v28
	v_mov_b32_e32 v16, v29
	v_pk_add_f32 v[80:81], v[80:81], v[82:83]
	v_pk_add_f32 v[16:17], v[78:79], v[16:17]
	ds_bpermute_b32 v85, v1, v84
	v_pk_add_f32 v[16:17], v[80:81], v[16:17]
	global_load_dwordx4 v[34:37], v[34:35], off offset:3072
	s_nop 0
	global_load_dwordx4 v[54:57], v[46:47], off
	s_nop 0
	global_load_dwordx4 v[46:49], v[74:75], off offset:1024
	global_load_dwordx4 v[50:53], v[74:75], off
	v_add_f32_e32 v16, v16, v17
	global_load_dwordx4 v[58:61], v[88:89], off offset:3072
	global_load_dwordx4 v[62:65], v[88:89], off offset:2048
	global_load_dwordx4 v[66:69], v[76:77], off offset:2048
	global_load_dwordx4 v[70:73], v[76:77], off offset:1024
	v_add_f32_dpp v16, v16, v16 quad_perm:[1,0,3,2] row_mask:0xf bank_mask:0xf bound_ctrl:1
	s_waitcnt lgkmcnt(0)
	v_add_f32_e32 v98, v84, v85
	ds_bpermute_b32 v99, v96, v98
	v_add_f32_dpp v16, v16, v16 quad_perm:[2,3,0,1] row_mask:0xf bank_mask:0xf bound_ctrl:1
	s_waitcnt lgkmcnt(0)
	v_add_f32_e32 v110, v98, v99
	v_add_f32_dpp v16, v16, v16 row_half_mirror row_mask:0xf bank_mask:0xf bound_ctrl:1
	v_fmamk_f32 v110, v110, 0x3a800000, v97
	s_nop 0
	v_add_f32_dpp v78, v16, v16 row_mirror row_mask:0xf bank_mask:0xf bound_ctrl:1
	ds_bpermute_b32 v79, v1, v78
	v_add_co_u32_e32 v16, vcc, s0, v88
	s_lshl_b64 s[0:1], s[24:25], 11
	s_nop 0
	v_addc_co_u32_e32 v17, vcc, 0, v89, vcc
	s_waitcnt lgkmcnt(0)
	v_add_f32_e32 v100, v78, v79
	ds_bpermute_b32 v101, v96, v100
	global_load_dwordx4 v[76:79], v[76:77], off offset:3072
	s_nop 0
	global_load_dwordx4 v[80:83], v[16:17], off
	global_load_dwordx4 v[84:87], v[88:89], off offset:1024
	s_nop 0
	global_load_dwordx4 v[88:91], v[88:89], off
	s_waitcnt lgkmcnt(0)
	v_add_f32_e32 v108, v100, v101
	v_fmamk_f32 v23, v108, 0xba800000, v23
	v_fmamk_f32 v22, v108, 0xba800000, v22
	v_fmamk_f32 v25, v108, 0xba800000, v25
	v_fmac_f32_e32 v24, 0xba800000, v108
	v_pk_mul_f32 v[16:17], v[24:25], v[24:25]
	v_pk_mul_f32 v[98:99], v[22:23], v[22:23]
	v_fmamk_f32 v21, v108, 0xba800000, v21
	v_pk_mov_b32 v[100:101], v[98:99], v[16:17] op_sel:[1,0]
	v_mov_b32_e32 v99, v17
	v_pk_add_f32 v[98:99], v[100:101], v[98:99]
	v_fmamk_f32 v101, v108, 0xba800000, v19
	v_fmamk_f32 v100, v108, 0xba800000, v18
	v_fmac_f32_e32 v20, 0xba800000, v108
	v_pk_mul_f32 v[16:17], v[20:21], v[20:21]
	v_pk_mul_f32 v[18:19], v[100:101], v[100:101]
	v_fmamk_f32 v104, v108, 0xba800000, v30
	v_pk_mov_b32 v[102:103], v[18:19], v[16:17] op_sel:[1,0]
	v_fmamk_f32 v105, v108, 0xba800000, v31
	v_mul_f32_e32 v16, v104, v104
	v_mov_b32_e32 v19, v17
	v_fmac_f32_e32 v32, 0xba800000, v108
	v_pk_fma_f32 v[16:17], v[104:105], v[104:105], v[16:17] op_sel_hi:[1,1,0]
	v_fmamk_f32 v33, v108, 0xba800000, v33
	v_mul_f32_e32 v16, v32, v32
	v_pk_add_f32 v[102:103], v[102:103], v[18:19]
	v_pk_fma_f32 v[18:19], v[32:33], v[32:33], v[16:17] op_sel_hi:[1,1,0]
	v_fmamk_f32 v27, v108, 0xba800000, v27
	v_fmac_f32_e32 v26, 0xba800000, v108
	v_mul_f32_e32 v16, v26, v26
	v_mul_f32_e32 v18, v27, v27
	v_fmamk_f32 v107, v108, 0xba800000, v29
	v_fmamk_f32 v106, v108, 0xba800000, v28
	v_pk_add_f32 v[108:109], v[16:17], v[18:19]
	global_load_dwordx4 v[16:19], v[74:75], off offset:3072
	global_load_dwordx4 v[28:31], v[74:75], off offset:2048
	v_pk_add_f32 v[74:75], v[98:99], v[98:99] op_sel_hi:[0,1]
	v_pk_add_f32 v[98:99], v[102:103], v[102:103] op_sel_hi:[0,1]
	v_mul_f32_e32 v74, v106, v106
	v_mul_f32_e32 v98, v107, v107
	v_pk_add_f32 v[74:75], v[74:75], v[98:99]
	v_rsq_f32_e32 v98, v110
	v_pk_add_f32 v[74:75], v[108:109], v[74:75]
	v_pk_mul_f32 v[6:7], v[6:7], v[98:99] op_sel_hi:[1,0]
	v_add_f32_e32 v74, v74, v75
	v_pk_mul_f32 v[8:9], v[8:9], v[98:99] op_sel_hi:[1,0]
	v_pk_mul_f32 v[2:3], v[2:3], v[98:99] op_sel_hi:[1,0]
	v_add_f32_dpp v74, v74, v74 quad_perm:[1,0,3,2] row_mask:0xf bank_mask:0xf bound_ctrl:1
	v_pk_mul_f32 v[4:5], v[4:5], v[98:99] op_sel_hi:[1,0]
	v_pk_mul_f32 v[10:11], v[10:11], v[98:99] op_sel_hi:[1,0]
	v_add_f32_dpp v74, v74, v74 quad_perm:[2,3,0,1] row_mask:0xf bank_mask:0xf bound_ctrl:1
	v_pk_mul_f32 v[12:13], v[12:13], v[98:99] op_sel_hi:[1,0]
	v_pk_mul_f32 v[14:15], v[14:15], v[98:99] op_sel_hi:[1,0]
	v_add_f32_dpp v74, v74, v74 row_half_mirror row_mask:0xf bank_mask:0xf bound_ctrl:1
	v_pk_mul_f32 v[94:95], v[94:95], v[98:99] op_sel_hi:[1,0]
	s_waitcnt vmcnt(4)
	v_pk_add_f32 v[80:81], v[80:81], 1.0 op_sel_hi:[1,0]
	v_add_f32_dpp v74, v74, v74 row_mirror row_mask:0xf bank_mask:0xf bound_ctrl:1
	ds_bpermute_b32 v1, v1, v74
	v_pk_add_f32 v[82:83], v[82:83], 1.0 op_sel_hi:[1,0]
	s_waitcnt vmcnt(2)
	v_pk_fma_f32 v[6:7], v[80:81], v[6:7], v[88:89]
	v_pk_fma_f32 v[8:9], v[82:83], v[8:9], v[90:91]
	v_cvt_pk_bf16_f32 v6, v6, v7
	s_waitcnt lgkmcnt(0)
	v_add_f32_e32 v1, v74, v1
	ds_bpermute_b32 v74, v96, v1
	v_cvt_pk_bf16_f32 v7, v8, v9
	v_pk_add_f32 v[8:9], v[70:71], 1.0 op_sel_hi:[1,0]
	s_waitcnt lgkmcnt(0)
	v_add_f32_e32 v1, v1, v74
	v_fmac_f32_e32 v97, 0x3a800000, v1
	v_rsq_f32_e32 v74, v97
	v_pk_fma_f32 v[2:3], v[8:9], v[2:3], v[84:85]
	v_pk_mul_f32 v[96:97], v[100:101], v[74:75] op_sel_hi:[1,0]
	v_lshl_add_u64 v[100:101], v[92:93], 0, s[0:1]
	global_store_dwordx2 v[100:101], v[6:7], off
	v_pk_add_f32 v[6:7], v[72:73], 1.0 op_sel_hi:[1,0]
	v_cvt_pk_bf16_f32 v2, v2, v3
	v_pk_mul_f32 v[22:23], v[22:23], v[74:75] op_sel_hi:[1,0]
	v_pk_fma_f32 v[4:5], v[6:7], v[4:5], v[86:87]
	v_pk_add_f32 v[6:7], v[54:55], 1.0 op_sel_hi:[1,0]
	v_cvt_pk_bf16_f32 v3, v4, v5
	v_pk_add_f32 v[4:5], v[66:67], 1.0 op_sel_hi:[1,0]
	global_store_dwordx2 v[100:101], v[2:3], off offset:512
	v_pk_add_f32 v[2:3], v[68:69], 1.0 op_sel_hi:[1,0]
	v_pk_fma_f32 v[4:5], v[4:5], v[10:11], v[62:63]
	v_pk_fma_f32 v[2:3], v[2:3], v[12:13], v[64:65]
	v_cvt_pk_bf16_f32 v4, v4, v5
	v_pk_mul_f32 v[24:25], v[24:25], v[74:75] op_sel_hi:[1,0]
	v_cvt_pk_bf16_f32 v5, v2, v3
	global_store_dwordx2 v[100:101], v[4:5], off offset:1024
	v_pk_add_f32 v[4:5], v[76:77], 1.0 op_sel_hi:[1,0]
	v_pk_add_f32 v[2:3], v[78:79], 1.0 op_sel_hi:[1,0]
	v_pk_fma_f32 v[4:5], v[4:5], v[14:15], v[58:59]
	v_pk_fma_f32 v[2:3], v[2:3], v[94:95], v[60:61]
	v_cvt_pk_bf16_f32 v4, v4, v5
	s_lshl_b64 s[0:1], s[22:23], 11
	v_cvt_pk_bf16_f32 v5, v2, v3
	global_store_dwordx2 v[100:101], v[4:5], off offset:1536
	v_pk_add_f32 v[4:5], v[56:57], 1.0 op_sel_hi:[1,0]
	v_pk_fma_f32 v[6:7], v[6:7], v[22:23], v[50:51]
	v_lshl_add_u64 v[2:3], v[92:93], 0, s[0:1]
	v_pk_fma_f32 v[4:5], v[4:5], v[24:25], v[52:53]
	v_cvt_pk_bf16_f32 v6, v6, v7
	v_pk_mul_f32 v[20:21], v[20:21], v[74:75] op_sel_hi:[1,0]
	v_cvt_pk_bf16_f32 v7, v4, v5
	global_store_dwordx2 v[2:3], v[6:7], off
	v_pk_add_f32 v[6:7], v[42:43], 1.0 op_sel_hi:[1,0]
	v_pk_add_f32 v[4:5], v[44:45], 1.0 op_sel_hi:[1,0]
	v_pk_fma_f32 v[6:7], v[6:7], v[96:97], v[46:47]
	v_pk_fma_f32 v[4:5], v[4:5], v[20:21], v[48:49]
	v_cvt_pk_bf16_f32 v6, v6, v7
	v_pk_mul_f32 v[98:99], v[104:105], v[74:75] op_sel_hi:[1,0]
	v_cvt_pk_bf16_f32 v7, v4, v5
	global_store_dwordx2 v[2:3], v[6:7], off offset:512
	v_pk_add_f32 v[6:7], v[38:39], 1.0 op_sel_hi:[1,0]
	v_pk_mul_f32 v[32:33], v[32:33], v[74:75] op_sel_hi:[1,0]
	v_pk_add_f32 v[4:5], v[40:41], 1.0 op_sel_hi:[1,0]
	s_waitcnt vmcnt(6)
	v_pk_fma_f32 v[6:7], v[6:7], v[98:99], v[28:29]
	v_pk_fma_f32 v[4:5], v[4:5], v[32:33], v[30:31]
	v_cvt_pk_bf16_f32 v6, v6, v7
	v_pk_mul_f32 v[26:27], v[26:27], v[74:75] op_sel_hi:[1,0]
	v_cvt_pk_bf16_f32 v7, v4, v5
	global_store_dwordx2 v[2:3], v[6:7], off offset:1024
	v_pk_add_f32 v[6:7], v[34:35], 1.0 op_sel_hi:[1,0]
	v_pk_mul_f32 v[74:75], v[106:107], v[74:75] op_sel_hi:[1,0]
	v_pk_add_f32 v[4:5], v[36:37], 1.0 op_sel_hi:[1,0]
	v_pk_fma_f32 v[6:7], v[6:7], v[26:27], v[16:17]
	v_pk_fma_f32 v[4:5], v[4:5], v[74:75], v[18:19]
	v_cvt_pk_bf16_f32 v6, v6, v7
	s_nop 0
	v_cvt_pk_bf16_f32 v7, v4, v5
	global_store_dwordx2 v[2:3], v[6:7], off offset:1536

.LBB0_291:
	s_ashr_i32 s3, s38, 5
	s_bfe_u32 s0, s38, 0x10003
	s_and_b32 s3, s3, 0x3ffffffe
	s_ashr_i32 s1, s38, 4
	s_or_b32 s3, s3, s0
	s_and_b32 s4, s1, 3
	s_lshl_b32 s3, s3, 2
	s_or_b32 s6, s3, s4
	s_ashr_i32 s7, s6, 31
	s_lshl_b64 s[6:7], s[6:7], 16
	s_add_u32 s5, s60, s6
	s_addc_u32 s7, s61, s7
	s_lshl_b32 s3, s38, 4
	s_and_b32 s3, s3, 0x70
	s_lshl_b32 s6, s3, 2
	v_ashrrev_i32_e32 v8, 2, v130
	s_add_u32 s6, s5, s6
	v_lshlrev_b32_e32 v2, 7, v8
	s_addc_u32 s7, s7, 0
	v_ashrrev_i32_e32 v3, 31, v2
	v_and_b32_e32 v4, 12, v141
	v_lshl_add_u64 v[2:3], v[2:3], 2, s[6:7]
	v_lshlrev_b32_e32 v6, 2, v4
	v_mov_b32_e32 v7, 0
	v_lshl_add_u64 v[2:3], v[2:3], 0, v[6:7]
	s_barrier
	global_load_dwordx4 v[2:5], v[2:3], off
	s_lshl_b32 s98, s4, 2
	s_lshl_b32 s99, s0, 4
	s_or_b32 s98, s99, s98
	v_readlane_b32 s100, v242, 4
	v_readlane_b32 s101, v242, 5
	v_mov_b32_e32 v240, s98
	s_nop 4
	global_load_dword v240, v240, s[100:101]
	v_cmp_eq_u32_e32 vcc, 0, v130
	s_and_saveexec_b64 s[6:7], vcc
	s_cbranch_execz .LBB0_306
	buffer_inv sc1
	s_lshl_b32 s8, s1, 6
	s_ashr_i32 s9, s8, 31
	s_lshl_b64 s[8:9], s[8:9], 2
	s_add_u32 s8, s82, s8
	s_addc_u32 s9, s83, s9
	s_mov_b32 s5, 0x100000
	s_branch .LBB0_295

.LBB0_295:
	global_load_dword v9, v7, s[8:9] sc1
	s_mov_b64 s[14:15], -1
	s_waitcnt vmcnt(0)
	v_cmp_lt_u32_e32 vcc, 7, v9
	s_cbranch_vccnz .LBB0_294
	s_cmp_lg_u32 s5, 0
	s_sleep 2
	s_cbranch_scc0 .LBB0_293
	global_load_dword v9, v7, s[8:9] sc1
	s_waitcnt vmcnt(0)
	v_cmp_gt_u32_e32 vcc, 8, v9
	s_cbranch_vccz .LBB0_294
	s_sleep 2
	global_load_dword v9, v7, s[8:9] sc1
	s_waitcnt vmcnt(0)
	v_cmp_gt_u32_e32 vcc, 8, v9
	s_cbranch_vccz .LBB0_294
	s_sleep 2
	global_load_dword v9, v7, s[8:9] sc1
	s_waitcnt vmcnt(0)
	v_cmp_gt_u32_e32 vcc, 8, v9
	s_cbranch_vccz .LBB0_294
	s_sleep 2
	global_load_dword v9, v7, s[8:9] sc1
	s_waitcnt vmcnt(0)
	v_cmp_gt_u32_e32 vcc, 8, v9
	s_cbranch_vccz .LBB0_294
	s_sleep 2
	global_load_dword v9, v7, s[8:9] sc1
	s_waitcnt vmcnt(0)
	v_cmp_gt_u32_e32 vcc, 8, v9
	s_cbranch_vccz .LBB0_294
	s_sleep 2
	global_load_dword v9, v7, s[8:9] sc1
	s_waitcnt vmcnt(0)
	v_cmp_gt_u32_e32 vcc, 8, v9
	s_cbranch_vccz .LBB0_294
	s_sleep 2
	global_load_dword v9, v7, s[8:9] sc1
	s_waitcnt vmcnt(0)
	v_cmp_gt_u32_e32 vcc, 8, v9
	s_cbranch_vccz .LBB0_294
	s_sleep 2
	s_add_i32 s5, s5, -8
	s_mov_b64 s[14:15], 0
	s_branch .LBB0_294
.LBB0_305:
	s_waitcnt vmcnt(0)
.LBB0_306:
	s_or_b64 exec, exec, s[6:7]
	s_movk_i32 s5, 0x44
	s_add_u32 s94, s54, 0xa800000
	v_mul_lo_u32 v7, v8, s5
	s_movk_i32 s5, 0x100
	s_addc_u32 s95, s55, 0
	v_add3_u32 v6, 0, v7, v6
	v_cmp_gt_i32_e32 vcc, s5, v130
	s_waitcnt vmcnt(0)
	ds_write2_b32 v6, v2, v3 offset1:1
	ds_write2_b32 v6, v4, v5 offset0:2 offset1:3
	s_waitcnt lgkmcnt(0)
	s_barrier
	s_and_saveexec_b64 s[8:9], vcc
	s_cbranch_execz .LBB0_308
	s_lshl_b32 s4, s4, 2
	s_lshl_b32 s5, s0, 4
	s_or_b32 s4, s5, s4
	v_readlane_b32 s16, v242, 0
	v_mov_b32_e32 v2, s4
	v_readlane_b32 s20, v242, 4
	v_readlane_b32 s21, v242, 5
	s_mov_b32 s6, 0xbfb8aa3b
	v_lshlrev_b32_e32 v3, 3, v130
	s_lshl_b32 s14, s1, 3
	s_lshl_b32 s1, s0, 15
	v_readlane_b32 s17, v242, 1
	v_mov_b32_e32 v8, v240
	v_add_lshl_u32 v2, v1, s3, 7
	v_readlane_b32 s18, v242, 2
	v_and_b32_e32 v11, 0x78, v3
	v_ashrrev_i32_e32 v3, 31, v2
	s_add_u32 s16, s92, s1
	v_readlane_b32 s19, v242, 3
	v_lshlrev_b64 v[36:37], 1, v[2:3]
	s_addc_u32 s17, s93, 0
	s_or_b32 s18, s14, 6
	s_or_b32 s20, s14, 7
	v_mov_b32_e32 v19, 0
	v_lshlrev_b32_e32 v18, 1, v11
	s_ashr_i32 s15, s14, 31
	v_lshl_add_u64 v[2:3], s[16:17], 0, v[36:37]
	s_ashr_i32 s19, s18, 31
	s_ashr_i32 s21, s20, 31
	s_lshl_b64 s[16:17], s[14:15], 16
	v_lshl_add_u64 v[14:15], v[2:3], 0, v[18:19]
	s_lshl_b64 s[18:19], s[18:19], 16
	s_lshl_b64 s[20:21], s[20:21], 16
	s_mov_b32 s5, 0x42ce8ed0
	v_lshl_add_u64 v[2:3], v[14:15], 0, s[16:17]
	v_lshl_add_u64 v[4:5], v[14:15], 0, s[18:19]
	v_lshl_add_u64 v[6:7], v[14:15], 0, s[20:21]
	s_mov_b32 s7, 0xc2b17218
	global_load_dwordx4 v[20:23], v[2:3], off
	s_nop 0
	global_load_dwordx4 v[2:5], v[4:5], off
	s_nop 0
	global_load_dwordx4 v[24:27], v[6:7], off
	v_mov_b32_e32 v9, 0x7f800000
	s_mov_b32 s10, 0x3f2aaaab
	s_mov_b32 s11, 0x3f317218
	v_mov_b32_e32 v10, 0x3ecc95a3
	s_mov_b32 s4, 0x7f800000
	s_mov_b32 s3, 0x33800000
	v_lshlrev_b32_e32 v1, 2, v1
	v_readlane_b32 s22, v242, 6
	v_readlane_b32 s23, v242, 7
	v_readlane_b32 s24, v242, 8
	v_readlane_b32 s25, v242, 9
	v_readlane_b32 s26, v242, 10
	v_readlane_b32 s27, v242, 11
	v_readlane_b32 s28, v242, 12
	v_readlane_b32 s29, v242, 13
	v_readlane_b32 s30, v242, 14
	v_readlane_b32 s31, v242, 15
	s_waitcnt vmcnt(3)
	v_mul_f32_e32 v12, 0xbfb8aa3b, v8
	v_fma_f32 v13, v8, s6, -v12
	v_rndne_f32_e32 v16, v12
	v_fmamk_f32 v13, v8, 0xb2a5705f, v13
	v_sub_f32_e32 v12, v12, v16
	v_add_f32_e32 v12, v12, v13
	v_cvt_i32_f32_e32 v16, v16
	v_exp_f32_e32 v12, v12
	v_cmp_nlt_f32_e32 vcc, s5, v8
	v_ldexp_f32 v6, v12, v16
	s_nop 0
	v_cndmask_b32_e32 v6, 0, v6, vcc
	v_cmp_ngt_f32_e32 vcc, s7, v8
	s_nop 1
	v_cndmask_b32_e32 v8, v9, v6, vcc
	v_add_f32_e32 v12, 1.0, v8
	v_add_f32_e32 v13, -1.0, v12
	v_frexp_mant_f32_e32 v16, v12
	v_cvt_f64_f32_e32 v[6:7], v12
	v_sub_f32_e32 v17, v13, v12
	v_frexp_exp_i32_f64_e32 v6, v[6:7]
	v_cmp_gt_f32_e32 vcc, s10, v16
	v_sub_f32_e32 v13, v8, v13
	v_add_f32_e32 v7, 1.0, v17
	v_subbrev_co_u32_e32 v6, vcc, 0, v6, vcc
	v_add_f32_e32 v7, v13, v7
	v_sub_u32_e32 v13, 0, v6
	v_cvt_f32_i32_e32 v6, v6
	v_ldexp_f32 v12, v12, v13
	v_ldexp_f32 v7, v7, v13
	v_add_f32_e32 v13, -1.0, v12
	v_add_f32_e32 v16, 1.0, v12
	v_add_f32_e32 v17, 1.0, v13
	v_add_f32_e32 v28, -1.0, v16
	v_sub_f32_e32 v17, v12, v17
	v_sub_f32_e32 v12, v12, v28
	v_mul_f32_e32 v28, 0x3f317218, v6
	v_add_f32_e32 v17, v7, v17
	v_add_f32_e32 v7, v7, v12
	v_fma_f32 v12, v6, s11, -v28
	v_add_f32_e32 v29, v13, v17
	v_add_f32_e32 v30, v16, v7
	v_fmamk_f32 v6, v6, 0xb102e308, v12
	v_sub_f32_e32 v12, v13, v29
	v_sub_f32_e32 v13, v16, v30
	v_rcp_f32_e32 v16, v30
	v_add_f32_e32 v31, v28, v6
	v_add_f32_e32 v7, v7, v13
	v_sub_f32_e32 v13, v31, v28
	v_sub_f32_e32 v6, v6, v13
	v_mul_f32_e32 v13, v29, v16
	v_add_f32_e32 v12, v17, v12
	v_mul_f32_e32 v17, v30, v13
	v_fma_f32 v28, v13, v30, -v17
	v_fmac_f32_e32 v28, v13, v7
	v_add_f32_e32 v32, v17, v28
	v_sub_f32_e32 v33, v29, v32
	v_sub_f32_e32 v17, v32, v17
	v_sub_f32_e32 v29, v29, v33
	v_sub_f32_e32 v17, v17, v28
	v_sub_f32_e32 v28, v29, v32
	v_add_f32_e32 v12, v12, v28
	v_add_f32_e32 v12, v17, v12
	v_add_f32_e32 v17, v33, v12
	v_mul_f32_e32 v28, v16, v17
	v_sub_f32_e32 v29, v33, v17
	v_mul_f32_e32 v32, v30, v28
	v_add_f32_e32 v12, v12, v29
	v_add_f32_e32 v29, v13, v28
	v_fma_f32 v30, v28, v30, -v32
	v_sub_f32_e32 v13, v29, v13
	v_fmac_f32_e32 v30, v28, v7
	v_sub_f32_e32 v7, v28, v13
	v_add_f32_e32 v13, v32, v30
	v_sub_f32_e32 v28, v13, v32
	v_sub_f32_e32 v32, v17, v13
	v_sub_f32_e32 v17, v17, v32
	v_sub_f32_e32 v13, v17, v13
	v_sub_f32_e32 v28, v28, v30
	v_add_f32_e32 v12, v12, v13
	v_add_f32_e32 v12, v28, v12
	v_add_f32_e32 v12, v32, v12
	v_mul_f32_e32 v12, v16, v12
	v_add_f32_e32 v7, v7, v12
	v_add_f32_e32 v12, v29, v7
	v_mul_f32_e32 v13, v12, v12
	v_fmac_f32_e32 v10, 0x3e9b6dac, v13
	v_sub_f32_e32 v16, v12, v29
	v_ldexp_f32 v17, v12, 1
	v_mul_f32_e32 v12, v12, v13
	v_fmaak_f32 v10, v13, v10, 0x3f2aaada
	v_mul_f32_e32 v10, v12, v10
	v_add_f32_e32 v12, v17, v10
	v_sub_f32_e32 v7, v7, v16
	v_sub_f32_e32 v13, v12, v17
	v_ldexp_f32 v7, v7, 1
	v_sub_f32_e32 v10, v10, v13
	v_add_f32_e32 v7, v7, v10
	v_add_f32_e32 v10, v12, v7
	v_sub_f32_e32 v12, v10, v12
	v_add_f32_e32 v13, v31, v10
	v_sub_f32_e32 v7, v7, v12
	v_sub_f32_e32 v12, v13, v31
	v_sub_f32_e32 v16, v13, v12
	v_sub_f32_e32 v10, v10, v12
	v_add_f32_e32 v12, v6, v7
	v_sub_f32_e32 v16, v31, v16
	v_sub_f32_e32 v17, v12, v6
	v_add_f32_e32 v10, v10, v16
	v_sub_f32_e32 v16, v12, v17
	v_sub_f32_e32 v6, v6, v16
	v_sub_f32_e32 v7, v7, v17
	v_add_f32_e32 v6, v7, v6
	v_add_f32_e32 v7, v12, v10
	v_add_f32_e32 v10, v13, v7
	v_sub_f32_e32 v12, v10, v13
	v_sub_f32_e32 v7, v7, v12
	v_add_f32_e32 v6, v6, v7
	v_add_f32_e32 v6, v10, v6
	v_cmp_neq_f32_e32 vcc, s4, v8
	s_or_b32 s4, s14, 1
	s_ashr_i32 s5, s4, 31
	v_cndmask_b32_e32 v6, v9, v6, vcc
	v_cmp_lt_f32_e64 vcc, |v8|, s3
	s_lshl_b64 s[4:5], s[4:5], 16
	s_nop 0
	v_cndmask_b32_e32 v6, v6, v8, vcc
	v_mul_f32_e32 v6, 0xbfb8aa3b, v6
	v_mul_f32_e32 v10, 0x43800000, v6
	v_lshl_add_u64 v[6:7], v[14:15], 0, s[4:5]
	s_or_b32 s4, s14, 2
	s_ashr_i32 s5, s4, 31
	v_exp_f32_e32 v50, v10
	v_mul_u32_u24_e32 v10, 0x44, v11
	s_lshl_b64 s[4:5], s[4:5], 16
	v_add3_u32 v1, 0, v1, v10
	v_lshl_add_u64 v[10:11], v[14:15], 0, s[4:5]
	s_or_b32 s4, s14, 3
	global_load_dwordx4 v[6:9], v[6:7], off
	s_ashr_i32 s5, s4, 31
	s_lshl_b64 s[4:5], s[4:5], 16
	v_lshl_add_u64 v[16:17], v[14:15], 0, s[4:5]
	s_or_b32 s4, s14, 4
	s_ashr_i32 s5, s4, 31
	s_lshl_b64 s[4:5], s[4:5], 16
	ds_read2_b32 v[40:41], v1 offset1:17
	ds_read2_b32 v[42:43], v1 offset0:34 offset1:51
	ds_read2_b32 v[44:45], v1 offset0:68 offset1:85
	ds_read2_b32 v[46:47], v1 offset0:102 offset1:119
	global_load_dwordx4 v[10:13], v[10:11], off
	s_nop 0
	global_load_dwordx4 v[28:31], v[16:17], off
	v_lshl_add_u64 v[16:17], v[14:15], 0, s[4:5]
	s_or_b32 s4, s14, 5
	s_ashr_i32 s5, s4, 31
	s_lshl_b64 s[4:5], s[4:5], 16
	v_lshl_add_u64 v[14:15], v[14:15], 0, s[4:5]
	global_load_dwordx4 v[32:35], v[16:17], off
	s_nop 0
	global_load_dwordx4 v[14:17], v[14:15], off
	s_add_u32 s4, s94, s1
	s_addc_u32 s5, s95, 0
	s_cmp_eq_u32 s0, 0
	s_cselect_b64 vcc, -1, 0
	v_lshl_add_u64 v[36:37], s[4:5], 0, v[36:37]
	s_and_b64 s[4:5], vcc, exec
	s_cselect_b32 s5, 0, 7
	s_cselect_b32 s10, 1, 6
	s_cselect_b32 s11, 2, 5
	s_cselect_b32 s4, 5, 2
	s_cselect_b32 s3, 6, 1
	s_cselect_b32 s1, 7, 0
	s_or_b32 s6, s5, s14
	s_ashr_i32 s7, s6, 31
	v_lshl_add_u64 v[18:19], v[36:37], 0, v[18:19]
	s_lshl_b64 s[6:7], s[6:7], 16
	v_lshl_add_u64 v[48:49], v[18:19], 0, s[6:7]
	s_waitcnt vmcnt(5)
	v_cndmask_b32_e32 v20, v24, v20, vcc
	s_or_b32 s6, s10, s14
	v_cndmask_b32_e32 v1, v27, v23, vcc
	v_cndmask_b32_e32 v22, v26, v22, vcc
	v_lshlrev_b32_e32 v26, 16, v20
	s_ashr_i32 s7, s6, 31
	s_waitcnt lgkmcnt(3)
	v_cvt_pk_bf16_f32 v36, v40, v41
	s_waitcnt lgkmcnt(2)
	v_cvt_pk_bf16_f32 v37, v42, v43
	s_waitcnt lgkmcnt(1)
	v_cvt_pk_bf16_f32 v38, v44, v45
	s_waitcnt lgkmcnt(0)
	v_cvt_pk_bf16_f32 v39, v46, v47
	v_cndmask_b32_e32 v21, v25, v21, vcc
	v_fmac_f32_e32 v26, v50, v40
	v_lshlrev_b32_e32 v40, 16, v1
	v_and_b32_e32 v1, 0xffff0000, v1
	s_lshl_b64 s[6:7], s[6:7], 16
	global_store_dwordx4 v[48:49], v[36:39], off
	v_and_b32_e32 v27, 0xffff0000, v20
	v_fmac_f32_e32 v40, v50, v46
	v_lshlrev_b32_e32 v36, 16, v21
	v_and_b32_e32 v37, 0xffff0000, v21
	v_lshlrev_b32_e32 v38, 16, v22
	v_and_b32_e32 v39, 0xffff0000, v22
	v_fmac_f32_e32 v1, v50, v47
	v_cvt_pk_bf16_f32 v23, v40, v1
	v_lshl_add_u64 v[24:25], v[18:19], 0, s[6:7]
	v_fmac_f32_e32 v27, v50, v41
	v_fmac_f32_e32 v36, v50, v42
	v_fmac_f32_e32 v37, v50, v43
	v_fmac_f32_e32 v38, v50, v44
	v_fmac_f32_e32 v39, v50, v45
	v_cvt_pk_bf16_f32 v20, v26, v27
	v_cvt_pk_bf16_f32 v21, v36, v37
	v_cvt_pk_bf16_f32 v22, v38, v39
	global_store_dwordx4 v[24:25], v[20:23], off
	s_or_b32 s6, s11, s14
	s_ashr_i32 s7, s6, 31
	s_lshl_b64 s[6:7], s[6:7], 16
	v_lshl_add_u64 v[24:25], v[18:19], 0, s[6:7]
	s_or_b32 s5, s0, s14
	s_add_i32 s6, s5, 3
	s_ashr_i32 s7, s6, 31
	s_lshl_b64 s[6:7], s[6:7], 16
	s_or_b32 s4, s4, s14
	s_ashr_i32 s5, s4, 31
	s_lshl_b64 s[4:5], s[4:5], 16
	s_waitcnt vmcnt(6)
	v_cndmask_b32_e32 v23, v2, v6, vcc
	v_lshlrev_b32_e32 v41, 16, v23
	v_cndmask_b32_e32 v22, v3, v7, vcc
	v_fmac_f32_e32 v41, v50, v26
	v_and_b32_e32 v26, 0xffff0000, v23
	v_fmac_f32_e32 v26, v50, v27
	v_lshlrev_b32_e32 v27, 16, v22
	v_cndmask_b32_e32 v21, v4, v8, vcc
	v_fmac_f32_e32 v27, v50, v36
	v_and_b32_e32 v36, 0xffff0000, v22
	v_fmac_f32_e32 v36, v50, v37
	v_lshlrev_b32_e32 v37, 16, v21
	v_cndmask_b32_e32 v20, v5, v9, vcc
	v_fmac_f32_e32 v37, v50, v38
	v_and_b32_e32 v38, 0xffff0000, v21
	v_fmac_f32_e32 v38, v50, v39
	v_lshlrev_b32_e32 v39, 16, v20
	v_fmac_f32_e32 v39, v50, v40
	v_and_b32_e32 v40, 0xffff0000, v20
	v_cvt_pk_bf16_f32 v22, v37, v38
	v_fmac_f32_e32 v40, v50, v1
	v_cvt_pk_bf16_f32 v20, v41, v26
	v_cvt_pk_bf16_f32 v21, v27, v36
	v_cvt_pk_bf16_f32 v23, v39, v40
	global_store_dwordx4 v[24:25], v[20:23], off
	s_waitcnt vmcnt(3)
	v_cndmask_b32_e32 v1, v17, v13, vcc
	v_lshl_add_u64 v[24:25], v[18:19], 0, s[6:7]
	v_cndmask_b32_e32 v22, v14, v10, vcc
	v_lshlrev_b32_e32 v42, 16, v22
	v_cndmask_b32_e32 v21, v15, v11, vcc
	v_fmac_f32_e32 v42, v50, v41
	v_and_b32_e32 v41, 0xffff0000, v22
	v_fmac_f32_e32 v41, v50, v26
	v_lshlrev_b32_e32 v26, 16, v21
	v_cndmask_b32_e32 v20, v16, v12, vcc
	v_fmac_f32_e32 v26, v50, v27
	v_and_b32_e32 v27, 0xffff0000, v21
	v_fmac_f32_e32 v27, v50, v36
	v_lshlrev_b32_e32 v36, 16, v20
	v_fmac_f32_e32 v36, v50, v37
	v_and_b32_e32 v37, 0xffff0000, v20
	v_fmac_f32_e32 v37, v50, v38
	v_lshlrev_b32_e32 v38, 16, v1
	v_and_b32_e32 v1, 0xffff0000, v1
	v_fmac_f32_e32 v38, v50, v39
	v_fmac_f32_e32 v1, v50, v40
	v_cvt_pk_bf16_f32 v23, v38, v1
	v_cvt_pk_bf16_f32 v20, v42, v41
	v_cvt_pk_bf16_f32 v21, v26, v27
	v_cvt_pk_bf16_f32 v22, v36, v37
	global_store_dwordx4 v[24:25], v[20:23], off
	s_sub_i32 s6, s14, s0
	s_ashr_i32 s7, s6, 31
	v_cndmask_b32_e32 v23, v32, v28, vcc
	v_cndmask_b32_e32 v22, v33, v29, vcc
	v_and_b32_e32 v40, 0xffff0000, v23
	v_fmac_f32_e32 v40, v50, v41
	v_lshlrev_b32_e32 v41, 16, v22
	v_cndmask_b32_e32 v21, v34, v30, vcc
	v_fmac_f32_e32 v41, v50, v26
	v_and_b32_e32 v26, 0xffff0000, v22
	v_fmac_f32_e32 v26, v50, v27
	v_lshlrev_b32_e32 v27, 16, v21
	s_lshl_b64 s[6:7], s[6:7], 16
	v_cndmask_b32_e32 v20, v35, v31, vcc
	v_fmac_f32_e32 v27, v50, v36
	v_and_b32_e32 v36, 0xffff0000, v21
	v_lshl_add_u64 v[24:25], v[18:19], 0, s[6:7]
	s_mov_b32 s0, 0x40000
	v_fmac_f32_e32 v36, v50, v37
	v_lshlrev_b32_e32 v37, 16, v20
	v_add_co_u32_e64 v24, s[6:7], s0, v24
	v_lshlrev_b32_e32 v39, 16, v23
	v_fmac_f32_e32 v37, v50, v38
	v_and_b32_e32 v38, 0xffff0000, v20
	v_cvt_pk_bf16_f32 v21, v41, v26
	v_addc_co_u32_e64 v25, s[6:7], 0, v25, s[6:7]
	v_fmac_f32_e32 v39, v50, v42
	v_fmac_f32_e32 v38, v50, v1
	v_cvt_pk_bf16_f32 v20, v39, v40
	v_cvt_pk_bf16_f32 v22, v27, v36
	v_cvt_pk_bf16_f32 v23, v37, v38
	global_store_dwordx4 v[24:25], v[20:23], off
	v_cndmask_b32_e32 v1, v31, v35, vcc
	v_lshl_add_u64 v[24:25], v[18:19], 0, s[4:5]
	v_cndmask_b32_e32 v21, v29, v33, vcc
	v_cndmask_b32_e32 v20, v30, v34, vcc
	v_and_b32_e32 v31, 0xffff0000, v21
	v_cndmask_b32_e32 v22, v28, v32, vcc
	v_fmac_f32_e32 v31, v50, v26
	v_lshlrev_b32_e32 v26, 16, v20
	v_lshlrev_b32_e32 v28, 16, v22
	v_and_b32_e32 v29, 0xffff0000, v22
	v_lshlrev_b32_e32 v30, 16, v21
	v_fmac_f32_e32 v26, v50, v27
	v_and_b32_e32 v27, 0xffff0000, v20
	v_lshlrev_b32_e32 v32, 16, v1
	v_and_b32_e32 v1, 0xffff0000, v1
	v_fmac_f32_e32 v28, v50, v39
	v_fmac_f32_e32 v29, v50, v40
	v_fmac_f32_e32 v30, v50, v41
	v_fmac_f32_e32 v27, v50, v36
	v_fmac_f32_e32 v32, v50, v37
	v_fmac_f32_e32 v1, v50, v38
	v_cvt_pk_bf16_f32 v20, v28, v29
	v_cvt_pk_bf16_f32 v21, v30, v31
	v_cvt_pk_bf16_f32 v22, v26, v27
	v_cvt_pk_bf16_f32 v23, v32, v1
	v_cndmask_b32_e32 v12, v12, v16, vcc
	v_cndmask_b32_e32 v11, v11, v15, vcc
	global_store_dwordx4 v[24:25], v[20:23], off
	v_cndmask_b32_e32 v13, v13, v17, vcc
	v_cndmask_b32_e32 v10, v10, v14, vcc
	v_lshlrev_b32_e32 v20, 16, v11
	v_and_b32_e32 v21, 0xffff0000, v11
	v_lshlrev_b32_e32 v22, 16, v12
	v_and_b32_e32 v23, 0xffff0000, v12
	s_or_b32 s4, s3, s14
	v_cndmask_b32_e32 v4, v8, v4, vcc
	v_cndmask_b32_e32 v3, v7, v3, vcc
	s_or_b32 s0, s1, s14
	v_lshlrev_b32_e32 v16, 16, v10
	v_and_b32_e32 v17, 0xffff0000, v10
	v_fmac_f32_e32 v20, v50, v30
	v_fmac_f32_e32 v21, v50, v31
	v_fmac_f32_e32 v22, v50, v26
	v_fmac_f32_e32 v23, v50, v27
	v_and_b32_e32 v25, 0xffff0000, v13
	s_ashr_i32 s5, s4, 31
	v_cndmask_b32_e32 v2, v6, v2, vcc
	v_lshlrev_b32_e32 v6, 16, v3
	v_and_b32_e32 v3, 0xffff0000, v3
	v_lshlrev_b32_e32 v7, 16, v4
	v_and_b32_e32 v4, 0xffff0000, v4
	s_ashr_i32 s1, s0, 31
	v_fmac_f32_e32 v16, v50, v28
	v_fmac_f32_e32 v17, v50, v29
	v_lshlrev_b32_e32 v24, 16, v13
	v_fmac_f32_e32 v25, v50, v1
	s_lshl_b64 s[4:5], s[4:5], 16
	v_cndmask_b32_e32 v1, v9, v5, vcc
	v_lshlrev_b32_e32 v5, 16, v2
	v_and_b32_e32 v2, 0xffff0000, v2
	v_fmac_f32_e32 v6, v50, v20
	v_fmac_f32_e32 v3, v50, v21
	v_fmac_f32_e32 v7, v50, v22
	v_fmac_f32_e32 v4, v50, v23
	s_lshl_b64 s[0:1], s[0:1], 16
	v_fmac_f32_e32 v24, v50, v32
	v_lshl_add_u64 v[14:15], v[18:19], 0, s[4:5]
	v_fmac_f32_e32 v5, v50, v16
	v_fmac_f32_e32 v2, v50, v17
	v_lshlrev_b32_e32 v8, 16, v1
	v_and_b32_e32 v1, 0xffff0000, v1
	v_cvt_pk_bf16_f32 v3, v6, v3
	v_cvt_pk_bf16_f32 v4, v7, v4
	v_lshl_add_u64 v[6:7], v[18:19], 0, s[0:1]
	v_cvt_pk_bf16_f32 v10, v16, v17
	v_cvt_pk_bf16_f32 v11, v20, v21
	v_cvt_pk_bf16_f32 v12, v22, v23
	v_cvt_pk_bf16_f32 v13, v24, v25
	global_store_dwordx4 v[14:15], v[10:13], off
	v_fmac_f32_e32 v8, v50, v24
	v_fmac_f32_e32 v1, v50, v25
	v_cvt_pk_bf16_f32 v2, v5, v2
	v_cvt_pk_bf16_f32 v5, v8, v1
	global_store_dwordx4 v[6:7], v[2:5], off

.LBB0_477:
	s_or_b64 exec, exec, s[4:5]
	s_cmp_gt_u32 s3, 63
	s_cbranch_scc1 .LBB0_494
	buffer_inv sc1
	s_memrealtime s[4:5]
	s_lshl_b32 s20, s86, 6
	s_ashr_i32 s21, s20, 31
	s_lshl_b64 s[20:21], s[20:21], 2
	s_add_u32 s20, s0, s20
	s_addc_u32 s21, s1, s21
	v_mov_b32_e32 v163, 0
	v_mov_b64_e32 v[164:165], 0x1e8481
	s_branch .LBB0_481

.LBB0_491:
	s_waitcnt vmcnt(0)
	s_and_b64 exec, exec, s[8:9]
	v_cndmask_b32_e64 v163, 0, 1, s[10:11]
	v_mov_b32_e32 v164, 0
	ds_write_b32 v164, v163 offset:32768

.LBB0_675:
	s_or_b64 exec, exec, s[10:11]
	s_cmp_gt_u32 s34, 63
	s_cbranch_scc1 .LBB0_692
	buffer_inv sc1
	s_memrealtime s[10:11]
	s_lshl_b32 s12, s6, 6
	s_ashr_i32 s13, s12, 31
	s_lshl_b64 s[12:13], s[12:13], 2
	s_add_u32 s12, s7, s12
	s_addc_u32 s13, s14, s13
	v_mov_b32_e32 v165, 0
	v_mov_b64_e32 v[162:163], 0x1e8481
	s_branch .LBB0_679

.LBB0_689:
	s_waitcnt vmcnt(0)
	s_and_b64 exec, exec, s[2:3]
	v_cndmask_b32_e64 v162, 0, 1, s[6:7]
	v_mov_b32_e32 v163, 0
	ds_write_b32 v163, v162 offset:10240
